# speedup vs baseline: 1.0126x; 1.0050x over previous
.Lbk64_350:
	s_waitcnt vmcnt(4)
	ds_read_b128 v[192:195], v227
	ds_read_b128 v[196:199], v228
	ds_read_b128 v[200:203], v227 offset:2048
	ds_read_b128 v[204:207], v228 offset:2048
	ds_read_b128 v[208:211], v227 offset:4096
	ds_read_b128 v[212:215], v228 offset:4096
	ds_read_b128 v[216:219], v227 offset:6144
	ds_read_b128 v[220:223], v228 offset:6144
	s_waitcnt vmcnt(0)
	s_barrier
	s_add_u32 s18, s18, 0x80
	s_addc_u32 s19, s19, 0
	s_add_u32 s16, s16, 0x80
	s_addc_u32 s17, s17, 0
	s_waitcnt lgkmcnt(0)
	ds_read_b128 v[154:157], v229 offset:0
	ds_read_b128 v[158:161], v230 offset:0
	ds_read_b128 v[162:165], v229 offset:2048
	ds_read_b128 v[166:169], v230 offset:2048
	s_waitcnt lgkmcnt(2)
	v_mfma_f32_16x16x32_bf16 v[126:129], v[192:195], v[154:157], v[126:129]
	v_mfma_f32_16x16x32_bf16 v[114:117], v[200:203], v[154:157], v[114:117]
	v_mfma_f32_16x16x32_bf16 v[86:89], v[208:211], v[154:157], v[86:89]
	v_mfma_f32_16x16x32_bf16 v[54:57], v[216:219], v[154:157], v[54:57]
	v_readfirstlane_b32 s32, v145
	s_lshl_b32 m0, s32, 3
	v_mov_b32_e32 v226, v224
	global_load_lds_dwordx4 v226, s[18:19]
	v_mfma_f32_16x16x32_bf16 v[126:129], v[196:199], v[158:161], v[126:129]
	v_mfma_f32_16x16x32_bf16 v[114:117], v[204:207], v[158:161], v[114:117]
	v_mfma_f32_16x16x32_bf16 v[86:89], v[212:215], v[158:161], v[86:89]
	v_mfma_f32_16x16x32_bf16 v[54:57], v[220:223], v[158:161], v[54:57]
	s_add_u32 m0, m0, 0x400
	v_add_u32_e32 v226, 0xac00, v224
	global_load_lds_dwordx4 v226, s[18:19]
	ds_read_b128 v[154:157], v229 offset:4096
	ds_read_b128 v[158:161], v230 offset:4096
	s_waitcnt lgkmcnt(2)
	v_mfma_f32_16x16x32_bf16 v[122:125], v[192:195], v[162:165], v[122:125]
	v_mfma_f32_16x16x32_bf16 v[102:105], v[200:203], v[162:165], v[102:105]
	v_mfma_f32_16x16x32_bf16 v[70:73], v[208:211], v[162:165], v[70:73]
	v_mfma_f32_16x16x32_bf16 v[38:41], v[216:219], v[162:165], v[38:41]
	s_add_u32 m0, m0, 0x400
	v_add_u32_e32 v226, 0x15800, v224
	global_load_lds_dwordx4 v226, s[18:19]
	v_mfma_f32_16x16x32_bf16 v[122:125], v[196:199], v[166:169], v[122:125]
	v_mfma_f32_16x16x32_bf16 v[102:105], v[204:207], v[166:169], v[102:105]
	v_mfma_f32_16x16x32_bf16 v[70:73], v[212:215], v[166:169], v[70:73]
	v_mfma_f32_16x16x32_bf16 v[38:41], v[220:223], v[166:169], v[38:41]
	s_add_u32 m0, m0, 0x400
	v_add_u32_e32 v226, 0x20400, v224
	global_load_lds_dwordx4 v226, s[18:19]
	ds_read_b128 v[162:165], v229 offset:6144
	ds_read_b128 v[166:169], v230 offset:6144
	s_waitcnt lgkmcnt(2)
	v_mfma_f32_16x16x32_bf16 v[118:121], v[192:195], v[154:157], v[118:121]
	v_mfma_f32_16x16x32_bf16 v[90:93], v[200:203], v[154:157], v[90:93]
	v_mfma_f32_16x16x32_bf16 v[58:61], v[208:211], v[154:157], v[58:61]
	v_mfma_f32_16x16x32_bf16 v[26:29], v[216:219], v[154:157], v[26:29]
	s_add_u32 m0, m0, 0x400
	v_add_u32_e32 v226, 0x2b000, v224
	global_load_lds_dwordx4 v226, s[18:19]
	v_mfma_f32_16x16x32_bf16 v[118:121], v[196:199], v[158:161], v[118:121]
	v_mfma_f32_16x16x32_bf16 v[90:93], v[204:207], v[158:161], v[90:93]
	v_mfma_f32_16x16x32_bf16 v[58:61], v[212:215], v[158:161], v[58:61]
	v_mfma_f32_16x16x32_bf16 v[26:29], v[220:223], v[158:161], v[26:29]
	s_add_u32 m0, m0, 0x400
	v_add_u32_e32 v226, 0x35c00, v224
	global_load_lds_dwordx4 v226, s[18:19]
	ds_read_b128 v[154:157], v229 offset:8192
	ds_read_b128 v[158:161], v230 offset:8192
	s_waitcnt lgkmcnt(2)
	v_mfma_f32_16x16x32_bf16 v[110:113], v[192:195], v[162:165], v[110:113]
	v_mfma_f32_16x16x32_bf16 v[78:81], v[200:203], v[162:165], v[78:81]
	v_mfma_f32_16x16x32_bf16 v[46:49], v[208:211], v[162:165], v[46:49]
	v_mfma_f32_16x16x32_bf16 v[18:21], v[216:219], v[162:165], v[18:21]
	s_add_u32 m0, m0, 0x400
	v_add_u32_e32 v226, 0x40800, v224
	global_load_lds_dwordx4 v226, s[18:19]
	v_mfma_f32_16x16x32_bf16 v[110:113], v[196:199], v[166:169], v[110:113]
	v_mfma_f32_16x16x32_bf16 v[78:81], v[204:207], v[166:169], v[78:81]
	v_mfma_f32_16x16x32_bf16 v[46:49], v[212:215], v[166:169], v[46:49]
	v_mfma_f32_16x16x32_bf16 v[18:21], v[220:223], v[166:169], v[18:21]
	s_add_u32 m0, m0, 0x400
	v_add_u32_e32 v226, 0x4b400, v224
	global_load_lds_dwordx4 v226, s[18:19]
	ds_read_b128 v[162:165], v229 offset:10240
	ds_read_b128 v[166:169], v230 offset:10240
	s_waitcnt lgkmcnt(2)
	v_mfma_f32_16x16x32_bf16 v[106:109], v[192:195], v[154:157], v[106:109]
	v_mfma_f32_16x16x32_bf16 v[74:77], v[200:203], v[154:157], v[74:77]
	v_mfma_f32_16x16x32_bf16 v[42:45], v[208:211], v[154:157], v[42:45]
	v_mfma_f32_16x16x32_bf16 v[14:17], v[216:219], v[154:157], v[14:17]
	s_add_u32 m0, s25, 44
	s_and_b32 m0, m0, 1
	s_lshl_b32 m0, m0, 14
	s_add_u32 m0, m0, 0x8000
	v_readfirstlane_b32 s32, v145
	s_lshl_b32 s32, s32, 2
	s_add_u32 m0, m0, s32
	v_mov_b32_e32 v226, v225
	global_load_lds_dwordx4 v226, s[16:17]
	v_mfma_f32_16x16x32_bf16 v[106:109], v[196:199], v[158:161], v[106:109]
	v_mfma_f32_16x16x32_bf16 v[74:77], v[204:207], v[158:161], v[74:77]
	v_mfma_f32_16x16x32_bf16 v[42:45], v[212:215], v[158:161], v[42:45]
	v_mfma_f32_16x16x32_bf16 v[14:17], v[220:223], v[158:161], v[14:17]
	s_add_u32 m0, m0, 0x400
	v_add_u32_e32 v226, 0xac00, v225
	global_load_lds_dwordx4 v226, s[16:17]
	ds_read_b128 v[154:157], v229 offset:12288
	ds_read_b128 v[158:161], v230 offset:12288
	s_waitcnt lgkmcnt(2)
	v_mfma_f32_16x16x32_bf16 v[98:101], v[192:195], v[162:165], v[98:101]
	v_mfma_f32_16x16x32_bf16 v[66:69], v[200:203], v[162:165], v[66:69]
	v_mfma_f32_16x16x32_bf16 v[34:37], v[208:211], v[162:165], v[34:37]
	v_mfma_f32_16x16x32_bf16 v[10:13], v[216:219], v[162:165], v[10:13]
	s_add_u32 m0, m0, 0x400
	v_add_u32_e32 v226, 0x15800, v225
	global_load_lds_dwordx4 v226, s[16:17]
	v_mfma_f32_16x16x32_bf16 v[98:101], v[196:199], v[166:169], v[98:101]
	v_mfma_f32_16x16x32_bf16 v[66:69], v[204:207], v[166:169], v[66:69]
	v_mfma_f32_16x16x32_bf16 v[34:37], v[212:215], v[166:169], v[34:37]
	v_mfma_f32_16x16x32_bf16 v[10:13], v[220:223], v[166:169], v[10:13]
	s_add_u32 m0, m0, 0x400
	v_add_u32_e32 v226, 0x20400, v225
	global_load_lds_dwordx4 v226, s[16:17]
	ds_read_b128 v[162:165], v229 offset:14336
	ds_read_b128 v[166:169], v230 offset:14336
	s_waitcnt lgkmcnt(2)
	v_mfma_f32_16x16x32_bf16 v[94:97], v[192:195], v[154:157], v[94:97]
	v_mfma_f32_16x16x32_bf16 v[62:65], v[200:203], v[154:157], v[62:65]
	v_mfma_f32_16x16x32_bf16 v[30:33], v[208:211], v[154:157], v[30:33]
	v_mfma_f32_16x16x32_bf16 v[6:9], v[216:219], v[154:157], v[6:9]
	v_mfma_f32_16x16x32_bf16 v[94:97], v[196:199], v[158:161], v[94:97]
	v_mfma_f32_16x16x32_bf16 v[62:65], v[204:207], v[158:161], v[62:65]
	v_mfma_f32_16x16x32_bf16 v[30:33], v[212:215], v[158:161], v[30:33]
	v_mfma_f32_16x16x32_bf16 v[6:9], v[220:223], v[158:161], v[6:9]
	s_waitcnt lgkmcnt(0)
	v_mfma_f32_16x16x32_bf16 v[82:85], v[192:195], v[162:165], v[82:85]
	v_mfma_f32_16x16x32_bf16 v[50:53], v[200:203], v[162:165], v[50:53]
	v_mfma_f32_16x16x32_bf16 v[22:25], v[208:211], v[162:165], v[22:25]
	v_mfma_f32_16x16x32_bf16 v[2:5], v[216:219], v[162:165], v[2:5]
	v_mfma_f32_16x16x32_bf16 v[82:85], v[196:199], v[166:169], v[82:85]
	v_mfma_f32_16x16x32_bf16 v[50:53], v[204:207], v[166:169], v[50:53]
	v_mfma_f32_16x16x32_bf16 v[22:25], v[212:215], v[166:169], v[22:25]
	v_mfma_f32_16x16x32_bf16 v[2:5], v[220:223], v[166:169], v[2:5]
	v_xor_b32_e32 v229, 0x4000, v229
	v_xor_b32_e32 v230, 0x4000, v230
	s_add_i32 s25, s25, 1
	s_cmp_lg_u32 s25, 42
	s_cbranch_scc1 .Lbk64_350
	s_waitcnt vmcnt(4)
	ds_read_b128 v[192:195], v227
	ds_read_b128 v[196:199], v228
	ds_read_b128 v[200:203], v227 offset:2048
	ds_read_b128 v[204:207], v228 offset:2048
	ds_read_b128 v[208:211], v227 offset:4096
	ds_read_b128 v[212:215], v228 offset:4096
	ds_read_b128 v[216:219], v227 offset:6144
	ds_read_b128 v[220:223], v228 offset:6144
	s_waitcnt vmcnt(0)
	s_barrier
	s_waitcnt lgkmcnt(0)
	ds_read_b128 v[154:157], v229 offset:0
	ds_read_b128 v[158:161], v230 offset:0
	ds_read_b128 v[162:165], v229 offset:2048
	ds_read_b128 v[166:169], v230 offset:2048
	s_waitcnt lgkmcnt(2)
	v_mfma_f32_16x16x32_bf16 v[126:129], v[192:195], v[154:157], v[126:129]
	v_mfma_f32_16x16x32_bf16 v[114:117], v[200:203], v[154:157], v[114:117]
	v_mfma_f32_16x16x32_bf16 v[86:89], v[208:211], v[154:157], v[86:89]
	v_mfma_f32_16x16x32_bf16 v[54:57], v[216:219], v[154:157], v[54:57]
	v_mfma_f32_16x16x32_bf16 v[126:129], v[196:199], v[158:161], v[126:129]
	v_mfma_f32_16x16x32_bf16 v[114:117], v[204:207], v[158:161], v[114:117]
	v_mfma_f32_16x16x32_bf16 v[86:89], v[212:215], v[158:161], v[86:89]
	v_mfma_f32_16x16x32_bf16 v[54:57], v[220:223], v[158:161], v[54:57]
	ds_read_b128 v[154:157], v229 offset:4096
	ds_read_b128 v[158:161], v230 offset:4096
	s_waitcnt lgkmcnt(2)
	v_mfma_f32_16x16x32_bf16 v[122:125], v[192:195], v[162:165], v[122:125]
	v_mfma_f32_16x16x32_bf16 v[102:105], v[200:203], v[162:165], v[102:105]
	v_mfma_f32_16x16x32_bf16 v[70:73], v[208:211], v[162:165], v[70:73]
	v_mfma_f32_16x16x32_bf16 v[38:41], v[216:219], v[162:165], v[38:41]
	v_mfma_f32_16x16x32_bf16 v[122:125], v[196:199], v[166:169], v[122:125]
	v_mfma_f32_16x16x32_bf16 v[102:105], v[204:207], v[166:169], v[102:105]
	v_mfma_f32_16x16x32_bf16 v[70:73], v[212:215], v[166:169], v[70:73]
	v_mfma_f32_16x16x32_bf16 v[38:41], v[220:223], v[166:169], v[38:41]
	ds_read_b128 v[162:165], v229 offset:6144
	ds_read_b128 v[166:169], v230 offset:6144
	s_waitcnt lgkmcnt(2)
	v_mfma_f32_16x16x32_bf16 v[118:121], v[192:195], v[154:157], v[118:121]
	v_mfma_f32_16x16x32_bf16 v[90:93], v[200:203], v[154:157], v[90:93]
	v_mfma_f32_16x16x32_bf16 v[58:61], v[208:211], v[154:157], v[58:61]
	v_mfma_f32_16x16x32_bf16 v[26:29], v[216:219], v[154:157], v[26:29]
	v_mfma_f32_16x16x32_bf16 v[118:121], v[196:199], v[158:161], v[118:121]
	v_mfma_f32_16x16x32_bf16 v[90:93], v[204:207], v[158:161], v[90:93]
	v_mfma_f32_16x16x32_bf16 v[58:61], v[212:215], v[158:161], v[58:61]
	v_mfma_f32_16x16x32_bf16 v[26:29], v[220:223], v[158:161], v[26:29]
	ds_read_b128 v[154:157], v229 offset:8192
	ds_read_b128 v[158:161], v230 offset:8192
	s_waitcnt lgkmcnt(2)
	v_mfma_f32_16x16x32_bf16 v[110:113], v[192:195], v[162:165], v[110:113]
	v_mfma_f32_16x16x32_bf16 v[78:81], v[200:203], v[162:165], v[78:81]
	v_mfma_f32_16x16x32_bf16 v[46:49], v[208:211], v[162:165], v[46:49]
	v_mfma_f32_16x16x32_bf16 v[18:21], v[216:219], v[162:165], v[18:21]
	v_mfma_f32_16x16x32_bf16 v[110:113], v[196:199], v[166:169], v[110:113]
	v_mfma_f32_16x16x32_bf16 v[78:81], v[204:207], v[166:169], v[78:81]
	v_mfma_f32_16x16x32_bf16 v[46:49], v[212:215], v[166:169], v[46:49]
	v_mfma_f32_16x16x32_bf16 v[18:21], v[220:223], v[166:169], v[18:21]
	ds_read_b128 v[162:165], v229 offset:10240
	ds_read_b128 v[166:169], v230 offset:10240
	s_waitcnt lgkmcnt(2)
	v_mfma_f32_16x16x32_bf16 v[106:109], v[192:195], v[154:157], v[106:109]
	v_mfma_f32_16x16x32_bf16 v[74:77], v[200:203], v[154:157], v[74:77]
	v_mfma_f32_16x16x32_bf16 v[42:45], v[208:211], v[154:157], v[42:45]
	v_mfma_f32_16x16x32_bf16 v[14:17], v[216:219], v[154:157], v[14:17]
	v_mfma_f32_16x16x32_bf16 v[106:109], v[196:199], v[158:161], v[106:109]
	v_mfma_f32_16x16x32_bf16 v[74:77], v[204:207], v[158:161], v[74:77]
	v_mfma_f32_16x16x32_bf16 v[42:45], v[212:215], v[158:161], v[42:45]
	v_mfma_f32_16x16x32_bf16 v[14:17], v[220:223], v[158:161], v[14:17]
	ds_read_b128 v[154:157], v229 offset:12288
	ds_read_b128 v[158:161], v230 offset:12288
	s_waitcnt lgkmcnt(2)
	v_mfma_f32_16x16x32_bf16 v[98:101], v[192:195], v[162:165], v[98:101]
	v_mfma_f32_16x16x32_bf16 v[66:69], v[200:203], v[162:165], v[66:69]
	v_mfma_f32_16x16x32_bf16 v[34:37], v[208:211], v[162:165], v[34:37]
	v_mfma_f32_16x16x32_bf16 v[10:13], v[216:219], v[162:165], v[10:13]
	v_mfma_f32_16x16x32_bf16 v[98:101], v[196:199], v[166:169], v[98:101]
	v_mfma_f32_16x16x32_bf16 v[66:69], v[204:207], v[166:169], v[66:69]
	v_mfma_f32_16x16x32_bf16 v[34:37], v[212:215], v[166:169], v[34:37]
	v_mfma_f32_16x16x32_bf16 v[10:13], v[220:223], v[166:169], v[10:13]
	ds_read_b128 v[162:165], v229 offset:14336
	ds_read_b128 v[166:169], v230 offset:14336
	s_waitcnt lgkmcnt(2)
	v_mfma_f32_16x16x32_bf16 v[94:97], v[192:195], v[154:157], v[94:97]
	v_mfma_f32_16x16x32_bf16 v[62:65], v[200:203], v[154:157], v[62:65]
	v_mfma_f32_16x16x32_bf16 v[30:33], v[208:211], v[154:157], v[30:33]
	v_mfma_f32_16x16x32_bf16 v[6:9], v[216:219], v[154:157], v[6:9]
	v_mfma_f32_16x16x32_bf16 v[94:97], v[196:199], v[158:161], v[94:97]
	v_mfma_f32_16x16x32_bf16 v[62:65], v[204:207], v[158:161], v[62:65]
	v_mfma_f32_16x16x32_bf16 v[30:33], v[212:215], v[158:161], v[30:33]
	v_mfma_f32_16x16x32_bf16 v[6:9], v[220:223], v[158:161], v[6:9]
	s_waitcnt lgkmcnt(0)
	v_mfma_f32_16x16x32_bf16 v[82:85], v[192:195], v[162:165], v[82:85]
	v_mfma_f32_16x16x32_bf16 v[50:53], v[200:203], v[162:165], v[50:53]
	v_mfma_f32_16x16x32_bf16 v[22:25], v[208:211], v[162:165], v[22:25]
	v_mfma_f32_16x16x32_bf16 v[2:5], v[216:219], v[162:165], v[2:5]
	v_mfma_f32_16x16x32_bf16 v[82:85], v[196:199], v[166:169], v[82:85]
	v_mfma_f32_16x16x32_bf16 v[50:53], v[204:207], v[166:169], v[50:53]
	v_mfma_f32_16x16x32_bf16 v[22:25], v[212:215], v[166:169], v[22:25]
	v_mfma_f32_16x16x32_bf16 v[2:5], v[220:223], v[166:169], v[2:5]
	s_nop 7
	s_nop 7
	s_waitcnt vmcnt(6)
	v_add_u32_e32 v145, v149, v147
	s_waitcnt vmcnt(0)
	s_waitcnt lgkmcnt(0)
	s_lshl_b32 s16, s5, 7
	s_ashr_i32 s17, s16, 31
	s_lshl_b64 s[16:17], s[16:17], 1
	v_and_b32_e32 v1, 0xfffffc0, v1
	v_lshl_or_b32 v1, v143, 2, v1
	v_mul_lo_u32 v1, v1, s33
	v_lshl_or_b32 v1, v142, 2, v1
	s_lshl_b32 s18, s5, 1
	s_ashr_i32 s19, s18, 31
	s_lshl_b64 s[18:19], s[18:19], 2
	s_add_i32 s24, s24, 1
	v_mov_b64_e32 v[158:159], v[62:63]
	v_mov_b64_e32 v[160:161], v[64:65]
	v_mov_b64_e32 v[162:163], v[30:31]
	v_mov_b64_e32 v[164:165], v[32:33]
	v_mov_b64_e32 v[130:131], v[22:23]
	v_mov_b64_e32 v[132:133], v[24:25]
	s_waitcnt lgkmcnt(0)
	v_mov_b64_e32 v[224:225], v[38:39]
	v_mov_b64_e32 v[226:227], v[40:41]
	v_mov_b64_e32 v[38:39], v[34:35]
	v_mov_b64_e32 v[40:41], v[36:37]
	v_mov_b64_e32 v[34:35], v[2:3]
	v_mov_b64_e32 v[36:37], v[4:5]
	s_nop 2
	v_mov_b32_e32 v2, v170
	v_mov_b64_e32 v[208:209], v[114:115]
	v_mov_b64_e32 v[210:211], v[116:117]
	v_add_u32_e32 v2, s4, v2
	v_ashrrev_i32_e32 v3, 31, v2
	v_lshlrev_b64 v[2:3], 11, v[2:3]
	v_lshl_add_u64 v[2:3], s[8:9], 0, v[2:3]
	v_lshl_add_u64 v[2:3], v[2:3], 0, s[16:17]
	v_mov_b64_e32 v[212:213], v[54:55]
	v_mov_b64_e32 v[214:215], v[56:57]
	v_mov_b64_e32 v[216:217], v[122:123]
	v_mov_b64_e32 v[218:219], v[124:125]
	v_mov_b64_e32 v[220:221], v[102:103]
	v_mov_b64_e32 v[222:223], v[104:105]
	v_mov_b64_e32 v[228:229], v[118:119]
	v_mov_b64_e32 v[230:231], v[120:121]
	v_mov_b64_e32 v[232:233], v[58:59]
	v_mov_b64_e32 v[234:235], v[60:61]
	v_mov_b64_e32 v[236:237], v[26:27]
	v_mov_b64_e32 v[238:239], v[28:29]
	v_mov_b64_e32 v[240:241], v[110:111]
	v_mov_b64_e32 v[242:243], v[112:113]
	v_mov_b64_e32 v[244:245], v[78:79]
	v_mov_b64_e32 v[246:247], v[80:81]
	v_mov_b64_e32 v[248:249], v[46:47]
	v_mov_b64_e32 v[250:251], v[48:49]
	v_mov_b64_e32 v[62:63], v[106:107]
	v_mov_b64_e32 v[64:65], v[108:109]
	v_mov_b64_e32 v[46:47], v[74:75]
	v_mov_b64_e32 v[48:49], v[76:77]
	v_mov_b64_e32 v[74:75], v[98:99]
	v_mov_b64_e32 v[76:77], v[100:101]
	v_mov_b64_e32 v[54:55], v[66:67]
	v_mov_b64_e32 v[56:57], v[68:69]
	v_mov_b64_e32 v[58:59], v[158:159]
	v_mov_b64_e32 v[60:61], v[160:161]
	v_mov_b64_e32 v[66:67], v[50:51]
	v_mov_b64_e32 v[68:69], v[52:53]
	flat_load_dwordx4 v[138:141], v[2:3]
	flat_load_dwordx4 v[122:125], v[2:3] offset:16
	flat_load_dwordx4 v[118:121], v[2:3] offset:32
	flat_load_dwordx4 v[114:117], v[2:3] offset:48
	flat_load_dwordx4 v[110:113], v[2:3] offset:64
	flat_load_dwordx4 v[106:109], v[2:3] offset:80
	flat_load_dwordx4 v[102:105], v[2:3] offset:96
	flat_load_dwordx4 v[98:101], v[2:3] offset:112
	s_waitcnt vmcnt(0) lgkmcnt(0)
	s_barrier
	s_nop 7
	ds_write2_b32 v1, v126, v216 offset1:16
	ds_write2_b32 v1, v127, v217 offset0:68 offset1:84
	ds_write2_b32 v1, v128, v218 offset0:136 offset1:152
	ds_write2_b32 v1, v129, v219 offset0:204 offset1:220
	ds_write2_b32 v1, v228, v240 offset0:32 offset1:48
	ds_write2_b32 v1, v229, v241 offset0:100 offset1:116
	ds_write2_b32 v1, v230, v242 offset0:168 offset1:184
	ds_write2_b32 v1, v231, v243 offset0:236 offset1:252
	v_mov_b64_e32 v[180:181], v[18:19]
	v_mov_b64_e32 v[182:183], v[20:21]
	v_mov_b64_e32 v[78:79], v[94:95]
	v_mov_b64_e32 v[80:81], v[96:97]
	v_add_u32_e32 v135, 0x3000, v1
	v_add_u32_e32 v134, 0x3400, v1
	v_mov_b32_e32 v136, v170
	v_mov_b64_e32 v[50:51], v[130:131]
	v_mov_b64_e32 v[52:53], v[132:133]
	v_lshlrev_b32_e32 v137, 16, v138
	s_nop 1
	v_add_u32_e32 v130, 0x1000, v1
	v_add_u32_e32 v131, 0x1400, v1
	v_add_u32_e32 v132, 0x2000, v1
	v_add_u32_e32 v133, 0x2400, v1
	ds_write2_b32 v130, v208, v220 offset0:64 offset1:80
	ds_write2_b32 v130, v209, v221 offset0:132 offset1:148
	ds_write2_b32 v130, v210, v222 offset0:200 offset1:216
	ds_write2_b32 v131, v211, v223 offset0:12 offset1:28
	ds_write2_b32 v130, v90, v244 offset0:96 offset1:112
	ds_write2_b32 v130, v91, v245 offset0:164 offset1:180
	ds_write2_b32 v130, v92, v246 offset0:232 offset1:248
	ds_write2_b32 v131, v93, v247 offset0:44 offset1:60
	ds_write2_b32 v132, v86, v70 offset0:128 offset1:144
	ds_write2_b32 v132, v87, v71 offset0:196 offset1:212
	ds_write2_b32 v133, v88, v72 offset0:8 offset1:24
	ds_write2_b32 v133, v89, v73 offset0:76 offset1:92
	ds_write2_b32 v132, v232, v248 offset0:160 offset1:176
	ds_write2_b32 v132, v233, v249 offset0:228 offset1:244
	ds_write2_b32 v133, v234, v250 offset0:40 offset1:56
	ds_write2_b32 v133, v235, v251 offset0:108 offset1:124
	ds_write2_b32 v135, v212, v224 offset0:192 offset1:208
	ds_write2_b32 v134, v213, v225 offset0:4 offset1:20
	ds_write2_b32 v134, v214, v226 offset0:72 offset1:88
	ds_write2_b32 v134, v215, v227 offset0:140 offset1:156
	ds_write2_b32 v135, v236, v180 offset0:224 offset1:240
	ds_write2_b32 v134, v237, v181 offset0:36 offset1:52
	ds_write2_b32 v134, v238, v182 offset0:104 offset1:120
	ds_write2_b32 v134, v239, v183 offset0:172 offset1:188
	s_waitcnt lgkmcnt(0)
	s_barrier
	v_mov_b64_e32 v[30:31], v[42:43]
	v_mov_b64_e32 v[32:33], v[44:45]
	v_add_u32_e32 v126, s4, v136
	v_ashrrev_i32_e32 v127, 31, v126
	v_lshlrev_b64 v[2:3], 11, v[126:127]
	v_lshl_add_u64 v[2:3], s[8:9], 0, v[2:3]
	v_lshl_add_u64 v[128:129], v[2:3], 0, s[16:17]
	v_mul_lo_u32 v136, v136, s33
	v_mov_b64_e32 v[18:19], v[14:15]
	v_mov_b64_e32 v[20:21], v[16:17]
	v_and_b32_e32 v138, 0xffff0000, v138
	v_mov_b64_e32 v[22:23], v[10:11]
	v_mov_b64_e32 v[24:25], v[12:13]
	v_mov_b64_e32 v[42:43], v[162:163]
	v_mov_b64_e32 v[44:45], v[164:165]
	v_mov_b64_e32 v[26:27], v[6:7]
	v_mov_b64_e32 v[28:29], v[8:9]
	flat_load_dwordx4 v[94:97], v[128:129] offset:128
	flat_load_dwordx4 v[90:93], v[128:129] offset:144
	flat_load_dwordx4 v[86:89], v[128:129] offset:160
	flat_load_dwordx4 v[70:73], v[128:129] offset:176
	flat_load_dwordx4 v[14:17], v[128:129] offset:192
	flat_load_dwordx4 v[10:13], v[128:129] offset:208
	flat_load_dwordx4 v[6:9], v[128:129] offset:224
	flat_load_dwordx4 v[2:5], v[128:129] offset:240
	ds_read_b128 v[142:145], v136
	ds_read_b128 v[154:157], v136 offset:16
	s_waitcnt lgkmcnt(0)
	v_add_f32_e32 v137, v142, v137
	v_add_f32_e32 v138, v143, v138
	v_cvt_pk_bf16_f32 v138, v137, v138
	v_lshlrev_b32_e32 v137, 16, v139
	v_and_b32_e32 v139, 0xffff0000, v139
	v_add_f32_e32 v137, v144, v137
	v_add_f32_e32 v139, v145, v139
	v_cvt_pk_bf16_f32 v139, v137, v139
	v_lshlrev_b32_e32 v137, 16, v140
	v_and_b32_e32 v140, 0xffff0000, v140
	v_add_f32_e32 v137, v154, v137
	v_add_f32_e32 v140, v155, v140
	v_cvt_pk_bf16_f32 v140, v137, v140
	v_lshlrev_b32_e32 v137, 16, v141
	v_and_b32_e32 v141, 0xffff0000, v141
	v_add_f32_e32 v137, v156, v137
	v_add_f32_e32 v141, v157, v141
	v_and_b32_e32 v142, 0xffff0000, v138
	v_cvt_pk_bf16_f32 v141, v137, v141
	v_lshlrev_b32_e32 v137, 16, v138
	v_mul_f32_e32 v153, v142, v142
	v_lshlrev_b32_e32 v143, 16, v139
	v_fmac_f32_e32 v153, v137, v137
	v_and_b32_e32 v144, 0xffff0000, v139
	v_fmac_f32_e32 v153, v143, v143
	v_lshlrev_b32_e32 v145, 16, v140
	v_fmac_f32_e32 v153, v144, v144
	ds_write_b128 v136, v[138:141]
	v_and_b32_e32 v147, 0xffff0000, v140
	v_lshlrev_b32_e32 v149, 16, v141
	v_and_b32_e32 v151, 0xffff0000, v141
	v_fmac_f32_e32 v153, v145, v145
	ds_read_b128 v[138:141], v136 offset:32
	ds_read_b128 v[142:145], v136 offset:48
	v_lshlrev_b32_e32 v137, 16, v122
	v_and_b32_e32 v122, 0xffff0000, v122
	v_fmac_f32_e32 v153, v147, v147
	s_waitcnt lgkmcnt(0)
	v_add_f32_e32 v137, v138, v137
	v_add_f32_e32 v122, v139, v122
	v_cvt_pk_bf16_f32 v122, v137, v122
	v_lshlrev_b32_e32 v137, 16, v123
	v_and_b32_e32 v123, 0xffff0000, v123
	v_add_f32_e32 v137, v140, v137
	v_add_f32_e32 v123, v141, v123
	v_cvt_pk_bf16_f32 v123, v137, v123
	v_lshlrev_b32_e32 v137, 16, v124
	v_and_b32_e32 v124, 0xffff0000, v124
	v_add_f32_e32 v137, v142, v137
	v_add_f32_e32 v124, v143, v124
	v_cvt_pk_bf16_f32 v124, v137, v124
	v_lshlrev_b32_e32 v137, 16, v125
	v_and_b32_e32 v125, 0xffff0000, v125
	v_add_f32_e32 v137, v144, v137
	v_add_f32_e32 v125, v145, v125
	v_and_b32_e32 v138, 0xffff0000, v122
	v_cvt_pk_bf16_f32 v125, v137, v125
	v_lshlrev_b32_e32 v137, 16, v122
	v_mul_f32_e32 v138, v138, v138
	v_lshlrev_b32_e32 v139, 16, v123
	v_fmac_f32_e32 v138, v137, v137
	v_and_b32_e32 v140, 0xffff0000, v123
	v_fmac_f32_e32 v138, v139, v139
	v_lshlrev_b32_e32 v141, 16, v124
	v_fmac_f32_e32 v138, v140, v140
	v_and_b32_e32 v142, 0xffff0000, v124
	v_fmac_f32_e32 v138, v141, v141
	v_lshlrev_b32_e32 v143, 16, v125
	v_fmac_f32_e32 v138, v142, v142
	v_fmac_f32_e32 v153, v149, v149
	v_and_b32_e32 v144, 0xffff0000, v125
	v_fmac_f32_e32 v138, v143, v143
	v_fmac_f32_e32 v153, v151, v151
	v_fmac_f32_e32 v138, v144, v144
	ds_write_b128 v136, v[122:125] offset:16
	v_add_f32_e32 v137, v153, v138
	ds_read_b128 v[122:125], v136 offset:64
	ds_read_b128 v[138:141], v136 offset:80
	v_lshlrev_b32_e32 v142, 16, v118
	v_and_b32_e32 v118, 0xffff0000, v118
	s_waitcnt lgkmcnt(0)
	v_add_f32_e32 v122, v122, v142
	v_add_f32_e32 v118, v123, v118
	v_cvt_pk_bf16_f32 v118, v122, v118
	v_lshlrev_b32_e32 v122, 16, v119
	v_and_b32_e32 v119, 0xffff0000, v119
	v_add_f32_e32 v122, v124, v122
	v_add_f32_e32 v119, v125, v119
	v_cvt_pk_bf16_f32 v119, v122, v119
	v_lshlrev_b32_e32 v122, 16, v120
	v_and_b32_e32 v120, 0xffff0000, v120
	v_add_f32_e32 v122, v138, v122
	v_add_f32_e32 v120, v139, v120
	v_cvt_pk_bf16_f32 v120, v122, v120
	v_lshlrev_b32_e32 v122, 16, v121
	v_and_b32_e32 v121, 0xffff0000, v121
	v_add_f32_e32 v122, v140, v122
	v_add_f32_e32 v121, v141, v121
	v_and_b32_e32 v123, 0xffff0000, v118
	v_cvt_pk_bf16_f32 v121, v122, v121
	v_lshlrev_b32_e32 v122, 16, v118
	v_mul_f32_e32 v123, v123, v123
	v_lshlrev_b32_e32 v124, 16, v119
	v_fmac_f32_e32 v123, v122, v122
	v_and_b32_e32 v125, 0xffff0000, v119
	v_fmac_f32_e32 v123, v124, v124
	v_lshlrev_b32_e32 v138, 16, v120
	v_fmac_f32_e32 v123, v125, v125
	v_and_b32_e32 v139, 0xffff0000, v120
	v_fmac_f32_e32 v123, v138, v138
	v_lshlrev_b32_e32 v140, 16, v121
	v_fmac_f32_e32 v123, v139, v139
	v_and_b32_e32 v141, 0xffff0000, v121
	v_fmac_f32_e32 v123, v140, v140
	v_fmac_f32_e32 v123, v141, v141
	ds_write_b128 v136, v[118:121] offset:32
	v_add_f32_e32 v137, v137, v123
	ds_read_b128 v[118:121], v136 offset:96
	ds_read_b128 v[122:125], v136 offset:112
	v_lshlrev_b32_e32 v138, 16, v114
	v_and_b32_e32 v114, 0xffff0000, v114
	s_waitcnt lgkmcnt(0)
	v_add_f32_e32 v118, v118, v138
	v_add_f32_e32 v114, v119, v114
	v_cvt_pk_bf16_f32 v114, v118, v114
	v_lshlrev_b32_e32 v118, 16, v115
	v_and_b32_e32 v115, 0xffff0000, v115
	v_add_f32_e32 v118, v120, v118
	v_add_f32_e32 v115, v121, v115
	v_cvt_pk_bf16_f32 v115, v118, v115
	v_lshlrev_b32_e32 v118, 16, v116
	v_and_b32_e32 v116, 0xffff0000, v116
	v_add_f32_e32 v118, v122, v118
	v_add_f32_e32 v116, v123, v116
	v_cvt_pk_bf16_f32 v116, v118, v116
	v_lshlrev_b32_e32 v118, 16, v117
	v_and_b32_e32 v117, 0xffff0000, v117
	v_add_f32_e32 v118, v124, v118
	v_add_f32_e32 v117, v125, v117
	v_and_b32_e32 v119, 0xffff0000, v114
	v_cvt_pk_bf16_f32 v117, v118, v117
	v_lshlrev_b32_e32 v118, 16, v114
	v_mul_f32_e32 v119, v119, v119
	v_lshlrev_b32_e32 v120, 16, v115
	v_fmac_f32_e32 v119, v118, v118
	v_and_b32_e32 v121, 0xffff0000, v115
	v_fmac_f32_e32 v119, v120, v120
	v_lshlrev_b32_e32 v122, 16, v116
	v_fmac_f32_e32 v119, v121, v121
	v_and_b32_e32 v123, 0xffff0000, v116
	v_fmac_f32_e32 v119, v122, v122
	v_lshlrev_b32_e32 v124, 16, v117
	v_fmac_f32_e32 v119, v123, v123
	v_and_b32_e32 v125, 0xffff0000, v117
	v_fmac_f32_e32 v119, v124, v124
	v_fmac_f32_e32 v119, v125, v125
	ds_write_b128 v136, v[114:117] offset:48
	v_add_f32_e32 v122, v137, v119
	ds_read_b128 v[114:117], v136 offset:128
	ds_read_b128 v[118:121], v136 offset:144
	v_lshlrev_b32_e32 v123, 16, v110
	v_and_b32_e32 v110, 0xffff0000, v110
	s_waitcnt lgkmcnt(0)
	v_add_f32_e32 v114, v114, v123
	v_add_f32_e32 v110, v115, v110
	v_cvt_pk_bf16_f32 v110, v114, v110
	v_lshlrev_b32_e32 v114, 16, v111
	v_and_b32_e32 v111, 0xffff0000, v111
	v_add_f32_e32 v114, v116, v114
	v_add_f32_e32 v111, v117, v111
	v_cvt_pk_bf16_f32 v111, v114, v111
	v_lshlrev_b32_e32 v114, 16, v112
	v_and_b32_e32 v112, 0xffff0000, v112
	v_add_f32_e32 v114, v118, v114
	v_add_f32_e32 v112, v119, v112
	v_cvt_pk_bf16_f32 v112, v114, v112
	v_lshlrev_b32_e32 v114, 16, v113
	v_and_b32_e32 v113, 0xffff0000, v113
	v_add_f32_e32 v114, v120, v114
	v_add_f32_e32 v113, v121, v113
	v_and_b32_e32 v115, 0xffff0000, v110
	v_cvt_pk_bf16_f32 v113, v114, v113
	v_lshlrev_b32_e32 v114, 16, v110
	v_mul_f32_e32 v115, v115, v115
	v_lshlrev_b32_e32 v116, 16, v111
	v_fmac_f32_e32 v115, v114, v114
	v_and_b32_e32 v117, 0xffff0000, v111
	v_fmac_f32_e32 v115, v116, v116
	v_lshlrev_b32_e32 v118, 16, v112
	v_fmac_f32_e32 v115, v117, v117
	v_and_b32_e32 v119, 0xffff0000, v112
	v_fmac_f32_e32 v115, v118, v118
	v_lshlrev_b32_e32 v120, 16, v113
	v_fmac_f32_e32 v115, v119, v119
	v_and_b32_e32 v121, 0xffff0000, v113
	v_fmac_f32_e32 v115, v120, v120
	v_fmac_f32_e32 v115, v121, v121
	ds_write_b128 v136, v[110:113] offset:64
	v_add_f32_e32 v118, v122, v115
	ds_read_b128 v[110:113], v136 offset:160
	ds_read_b128 v[114:117], v136 offset:176
	v_lshlrev_b32_e32 v119, 16, v106
	v_and_b32_e32 v106, 0xffff0000, v106
	s_waitcnt lgkmcnt(0)
	v_add_f32_e32 v110, v110, v119
	v_add_f32_e32 v106, v111, v106
	v_cvt_pk_bf16_f32 v106, v110, v106
	v_lshlrev_b32_e32 v110, 16, v107
	v_and_b32_e32 v107, 0xffff0000, v107
	v_add_f32_e32 v110, v112, v110
	v_add_f32_e32 v107, v113, v107
	v_cvt_pk_bf16_f32 v107, v110, v107
	v_lshlrev_b32_e32 v110, 16, v108
	v_and_b32_e32 v108, 0xffff0000, v108
	v_add_f32_e32 v110, v114, v110
	v_add_f32_e32 v108, v115, v108
	v_cvt_pk_bf16_f32 v108, v110, v108
	v_lshlrev_b32_e32 v110, 16, v109
	v_and_b32_e32 v109, 0xffff0000, v109
	v_add_f32_e32 v110, v116, v110
	v_add_f32_e32 v109, v117, v109
	v_and_b32_e32 v111, 0xffff0000, v106
	v_cvt_pk_bf16_f32 v109, v110, v109
	v_lshlrev_b32_e32 v110, 16, v106
	v_mul_f32_e32 v111, v111, v111
	v_lshlrev_b32_e32 v112, 16, v107
	v_fmac_f32_e32 v111, v110, v110
	v_and_b32_e32 v113, 0xffff0000, v107
	v_fmac_f32_e32 v111, v112, v112
	v_lshlrev_b32_e32 v114, 16, v108
	v_fmac_f32_e32 v111, v113, v113
	v_and_b32_e32 v115, 0xffff0000, v108
	v_fmac_f32_e32 v111, v114, v114
	v_lshlrev_b32_e32 v116, 16, v109
	v_fmac_f32_e32 v111, v115, v115
	v_and_b32_e32 v117, 0xffff0000, v109
	v_fmac_f32_e32 v111, v116, v116
	v_fmac_f32_e32 v111, v117, v117
	ds_write_b128 v136, v[106:109] offset:80
	v_add_f32_e32 v114, v118, v111
	ds_read_b128 v[106:109], v136 offset:192
	ds_read_b128 v[110:113], v136 offset:208
	v_lshlrev_b32_e32 v115, 16, v102
	v_and_b32_e32 v102, 0xffff0000, v102
	s_waitcnt lgkmcnt(0)
	v_add_f32_e32 v106, v106, v115
	v_add_f32_e32 v102, v107, v102
	v_cvt_pk_bf16_f32 v102, v106, v102
	v_lshlrev_b32_e32 v106, 16, v103
	v_and_b32_e32 v103, 0xffff0000, v103
	v_add_f32_e32 v106, v108, v106
	v_add_f32_e32 v103, v109, v103
	v_cvt_pk_bf16_f32 v103, v106, v103
	v_lshlrev_b32_e32 v106, 16, v104
	v_and_b32_e32 v104, 0xffff0000, v104
	v_add_f32_e32 v106, v110, v106
	v_add_f32_e32 v104, v111, v104
	v_cvt_pk_bf16_f32 v104, v106, v104
	v_lshlrev_b32_e32 v106, 16, v105
	v_and_b32_e32 v105, 0xffff0000, v105
	v_add_f32_e32 v106, v112, v106
	v_add_f32_e32 v105, v113, v105
	v_and_b32_e32 v107, 0xffff0000, v102
	v_cvt_pk_bf16_f32 v105, v106, v105
	v_lshlrev_b32_e32 v106, 16, v102
	v_mul_f32_e32 v107, v107, v107
	v_lshlrev_b32_e32 v108, 16, v103
	v_fmac_f32_e32 v107, v106, v106
	v_and_b32_e32 v109, 0xffff0000, v103
	v_fmac_f32_e32 v107, v108, v108
	v_lshlrev_b32_e32 v110, 16, v104
	v_fmac_f32_e32 v107, v109, v109
	v_and_b32_e32 v111, 0xffff0000, v104
	v_fmac_f32_e32 v107, v110, v110
	v_lshlrev_b32_e32 v112, 16, v105
	v_fmac_f32_e32 v107, v111, v111
	v_and_b32_e32 v113, 0xffff0000, v105
	v_fmac_f32_e32 v107, v112, v112
	v_fmac_f32_e32 v107, v113, v113
	ds_write_b128 v136, v[102:105] offset:96
	v_add_f32_e32 v110, v114, v107
	ds_read_b128 v[102:105], v136 offset:224
	ds_read_b128 v[106:109], v136 offset:240
	v_lshlrev_b32_e32 v111, 16, v98
	v_and_b32_e32 v98, 0xffff0000, v98
	s_waitcnt lgkmcnt(0)
	v_add_f32_e32 v102, v102, v111
	v_add_f32_e32 v98, v103, v98
	v_cvt_pk_bf16_f32 v98, v102, v98
	v_lshlrev_b32_e32 v102, 16, v99
	v_and_b32_e32 v99, 0xffff0000, v99
	v_add_f32_e32 v102, v104, v102
	v_add_f32_e32 v99, v105, v99
	v_cvt_pk_bf16_f32 v99, v102, v99
	v_lshlrev_b32_e32 v102, 16, v100
	v_and_b32_e32 v100, 0xffff0000, v100
	v_add_f32_e32 v102, v106, v102
	v_add_f32_e32 v100, v107, v100
	v_cvt_pk_bf16_f32 v100, v102, v100
	v_lshlrev_b32_e32 v102, 16, v101
	v_and_b32_e32 v101, 0xffff0000, v101
	v_add_f32_e32 v102, v108, v102
	v_add_f32_e32 v101, v109, v101
	v_and_b32_e32 v103, 0xffff0000, v98
	v_cvt_pk_bf16_f32 v101, v102, v101
	v_lshlrev_b32_e32 v102, 16, v98
	v_mul_f32_e32 v103, v103, v103
	v_lshlrev_b32_e32 v104, 16, v99
	v_fmac_f32_e32 v103, v102, v102
	v_and_b32_e32 v105, 0xffff0000, v99
	v_fmac_f32_e32 v103, v104, v104
	v_lshlrev_b32_e32 v106, 16, v100
	v_fmac_f32_e32 v103, v105, v105
	v_and_b32_e32 v107, 0xffff0000, v100
	v_fmac_f32_e32 v103, v106, v106
	v_lshlrev_b32_e32 v108, 16, v101
	v_fmac_f32_e32 v103, v107, v107
	v_and_b32_e32 v109, 0xffff0000, v101
	v_fmac_f32_e32 v103, v108, v108
	ds_write_b128 v136, v[98:101] offset:112
	v_and_b32_e32 v102, 63, v170
	v_lshrrev_b32_e32 v108, 3, v102
	v_sub_u32_e32 v108, v108, v102
	v_and_b32_e32 v102, 7, v102
	v_lshlrev_b32_e32 v102, 4, v102
	v_mul_i32_i24_e32 v98, 0x800, v108
	v_add_u32_e32 v98, v98, v102
	v_mul_i32_i24_e32 v108, 0x110, v108
	v_add3_u32 v108, v108, v102, v136
	s_waitcnt lgkmcnt(0)
	ds_read_b128 v[104:107], v108 offset:0
	v_mov_b32_e32 v100, v98
	v_ashrrev_i32_e32 v101, 31, v100
	v_lshl_add_u64 v[116:117], v[100:101], 0, v[128:129]
	s_waitcnt lgkmcnt(0)
	global_store_dwordx4 v[116:117], v[104:107], off
	ds_read_b128 v[112:115], v108 offset:2176
	v_add_u32_e32 v100, 0x4000, v98
	v_ashrrev_i32_e32 v101, 31, v100
	v_lshl_add_u64 v[116:117], v[100:101], 0, v[128:129]
	s_waitcnt lgkmcnt(0)
	global_store_dwordx4 v[116:117], v[112:115], off
	ds_read_b128 v[104:107], v108 offset:4352
	v_add_u32_e32 v100, 0x8000, v98
	v_ashrrev_i32_e32 v101, 31, v100
	v_lshl_add_u64 v[116:117], v[100:101], 0, v[128:129]
	s_waitcnt lgkmcnt(0)
	global_store_dwordx4 v[116:117], v[104:107], off
	ds_read_b128 v[112:115], v108 offset:6528
	v_add_u32_e32 v100, 0xc000, v98
	v_ashrrev_i32_e32 v101, 31, v100
	v_lshl_add_u64 v[116:117], v[100:101], 0, v[128:129]
	s_waitcnt lgkmcnt(0)
	global_store_dwordx4 v[116:117], v[112:115], off
	ds_read_b128 v[104:107], v108 offset:8704
	v_add_u32_e32 v100, 0x10000, v98
	v_ashrrev_i32_e32 v101, 31, v100
	v_lshl_add_u64 v[116:117], v[100:101], 0, v[128:129]
	s_waitcnt lgkmcnt(0)
	global_store_dwordx4 v[116:117], v[104:107], off
	ds_read_b128 v[112:115], v108 offset:10880
	v_add_u32_e32 v100, 0x14000, v98
	v_ashrrev_i32_e32 v101, 31, v100
	v_lshl_add_u64 v[116:117], v[100:101], 0, v[128:129]
	s_waitcnt lgkmcnt(0)
	global_store_dwordx4 v[116:117], v[112:115], off
	ds_read_b128 v[104:107], v108 offset:13056
	v_add_u32_e32 v100, 0x18000, v98
	v_ashrrev_i32_e32 v101, 31, v100
	v_lshl_add_u64 v[116:117], v[100:101], 0, v[128:129]
	s_waitcnt lgkmcnt(0)
	global_store_dwordx4 v[116:117], v[104:107], off
	ds_read_b128 v[112:115], v108 offset:15232
	v_add_u32_e32 v100, 0x1c000, v98
	v_ashrrev_i32_e32 v101, 31, v100
	v_lshl_add_u64 v[116:117], v[100:101], 0, v[128:129]
	s_waitcnt lgkmcnt(0)
	global_store_dwordx4 v[116:117], v[112:115], off
	v_fmac_f32_e32 v103, v109, v109
	v_add_f32_e32 v102, v110, v103
	v_lshlrev_b64 v[98:99], 6, v[126:127]
	v_lshl_add_u64 v[98:99], s[6:7], 0, v[98:99]
	v_lshl_add_u64 v[98:99], v[98:99], 0, s[18:19]
	flat_store_dword v[98:99], v102
	s_waitcnt lgkmcnt(0)
	s_barrier
	ds_write2_b32 v1, v62, v74 offset1:16
	ds_write2_b32 v1, v63, v75 offset0:68 offset1:84
	ds_write2_b32 v1, v64, v76 offset0:136 offset1:152
	ds_write2_b32 v1, v65, v77 offset0:204 offset1:220
	ds_write2_b32 v1, v78, v82 offset0:32 offset1:48
	ds_write2_b32 v1, v79, v83 offset0:100 offset1:116
	ds_write2_b32 v1, v80, v84 offset0:168 offset1:184
	ds_write2_b32 v1, v81, v85 offset0:236 offset1:252
	ds_write2_b32 v130, v46, v54 offset0:64 offset1:80
	ds_write2_b32 v130, v47, v55 offset0:132 offset1:148
	ds_write2_b32 v130, v48, v56 offset0:200 offset1:216
	ds_write2_b32 v131, v49, v57 offset0:12 offset1:28
	ds_write2_b32 v130, v58, v66 offset0:96 offset1:112
	ds_write2_b32 v130, v59, v67 offset0:164 offset1:180
	ds_write2_b32 v130, v60, v68 offset0:232 offset1:248
	ds_write2_b32 v131, v61, v69 offset0:44 offset1:60
	ds_write2_b32 v132, v30, v38 offset0:128 offset1:144
	ds_write2_b32 v132, v31, v39 offset0:196 offset1:212
	ds_write2_b32 v133, v32, v40 offset0:8 offset1:24
	ds_write2_b32 v133, v33, v41 offset0:76 offset1:92
	ds_write2_b32 v132, v42, v50 offset0:160 offset1:176
	ds_write2_b32 v132, v43, v51 offset0:228 offset1:244
	ds_write2_b32 v133, v44, v52 offset0:40 offset1:56
	ds_write2_b32 v133, v45, v53 offset0:108 offset1:124
	ds_write2_b32 v135, v18, v22 offset0:192 offset1:208
	ds_write2_b32 v134, v19, v23 offset0:4 offset1:20
	ds_write2_b32 v134, v20, v24 offset0:72 offset1:88
	ds_write2_b32 v134, v21, v25 offset0:140 offset1:156
	ds_write2_b32 v135, v26, v34 offset0:224 offset1:240
	ds_write2_b32 v134, v27, v35 offset0:36 offset1:52
	ds_write2_b32 v134, v28, v36 offset0:104 offset1:120
	ds_write2_b32 v134, v29, v37 offset0:172 offset1:188
	v_mov_b32_e32 v1, v170
	s_waitcnt lgkmcnt(0)
	s_barrier
	s_waitcnt vmcnt(0)
	v_lshlrev_b32_e32 v28, 16, v94
	v_add_u32_e32 v18, s4, v1
	v_ashrrev_i32_e32 v19, 31, v18
	v_lshlrev_b64 v[20:21], 11, v[18:19]
	v_lshl_add_u64 v[20:21], s[38:39], 0, v[20:21]
	v_mul_lo_u32 v1, v1, s33
	v_lshl_add_u64 v[32:33], v[20:21], 0, s[16:17]
	ds_read_b128 v[20:23], v1
	ds_read_b128 v[24:27], v1 offset:16
	s_mov_b64 s[4:5], 0
	s_waitcnt lgkmcnt(1)
	v_add_f32_e32 v20, v20, v28
	v_and_b32_e32 v28, 0xffff0000, v94
	v_add_f32_e32 v21, v21, v28
	v_cvt_pk_bf16_f32 v28, v20, v21
	v_and_b32_e32 v21, 0xffff0000, v95
	v_lshlrev_b32_e32 v20, 16, v95
	v_add_f32_e32 v21, v23, v21
	v_add_f32_e32 v20, v22, v20
	v_cvt_pk_bf16_f32 v29, v20, v21
	v_and_b32_e32 v21, 0xffff0000, v96
	v_lshlrev_b32_e32 v20, 16, v96
	s_waitcnt lgkmcnt(0)
	v_add_f32_e32 v21, v25, v21
	v_add_f32_e32 v20, v24, v20
	v_cvt_pk_bf16_f32 v30, v20, v21
	v_and_b32_e32 v21, 0xffff0000, v97
	v_lshlrev_b32_e32 v20, 16, v97
	v_add_f32_e32 v21, v27, v21
	v_add_f32_e32 v20, v26, v20
	v_cvt_pk_bf16_f32 v31, v20, v21
	v_and_b32_e32 v21, 0xffff0000, v28
	v_lshlrev_b32_e32 v20, 16, v28
	v_mul_f32_e32 v34, v21, v21
	v_lshlrev_b32_e32 v22, 16, v29
	v_fmac_f32_e32 v34, v20, v20
	v_and_b32_e32 v23, 0xffff0000, v29
	v_fmac_f32_e32 v34, v22, v22
	v_lshlrev_b32_e32 v24, 16, v30
	v_fmac_f32_e32 v34, v23, v23
	v_and_b32_e32 v25, 0xffff0000, v30
	v_fmac_f32_e32 v34, v24, v24
	v_add_co_u32_e32 v20, vcc, s90, v32
	v_lshlrev_b32_e32 v26, 16, v31
	v_fmac_f32_e32 v34, v25, v25
	v_addc_co_u32_e32 v21, vcc, 0, v33, vcc
	v_and_b32_e32 v27, 0xffff0000, v31
	v_fmac_f32_e32 v34, v26, v26
	v_mul_u32_u24_e32 v35, 0x110, v170
	ds_write_b128 v35, v[28:31]
	v_fmac_f32_e32 v34, v27, v27
	ds_read_b128 v[22:25], v1 offset:32
	ds_read_b128 v[26:29], v1 offset:48
	v_lshlrev_b32_e32 v30, 16, v90
	s_waitcnt lgkmcnt(0)
	v_add_f32_e32 v22, v22, v30
	v_and_b32_e32 v30, 0xffff0000, v90
	v_add_f32_e32 v23, v23, v30
	v_cvt_pk_bf16_f32 v22, v22, v23
	v_lshlrev_b32_e32 v23, 16, v91
	v_add_f32_e32 v23, v24, v23
	v_and_b32_e32 v24, 0xffff0000, v91
	v_add_f32_e32 v24, v25, v24
	v_cvt_pk_bf16_f32 v23, v23, v24
	v_lshlrev_b32_e32 v24, 16, v92
	v_and_b32_e32 v25, 0xffff0000, v92
	v_add_f32_e32 v24, v26, v24
	v_add_f32_e32 v25, v27, v25
	v_cvt_pk_bf16_f32 v24, v24, v25
	v_lshlrev_b32_e32 v25, 16, v93
	v_and_b32_e32 v26, 0xffff0000, v93
	v_add_f32_e32 v25, v28, v25
	v_add_f32_e32 v26, v29, v26
	v_and_b32_e32 v27, 0xffff0000, v22
	v_cvt_pk_bf16_f32 v25, v25, v26
	v_lshlrev_b32_e32 v26, 16, v22
	v_mul_f32_e32 v27, v27, v27
	v_lshlrev_b32_e32 v28, 16, v23
	v_fmac_f32_e32 v27, v26, v26
	v_and_b32_e32 v29, 0xffff0000, v23
	v_fmac_f32_e32 v27, v28, v28
	v_lshlrev_b32_e32 v30, 16, v24
	v_fmac_f32_e32 v27, v29, v29
	v_and_b32_e32 v31, 0xffff0000, v24
	v_fmac_f32_e32 v27, v30, v30
	v_lshlrev_b32_e32 v32, 16, v25
	v_fmac_f32_e32 v27, v31, v31
	v_and_b32_e32 v33, 0xffff0000, v25
	v_fmac_f32_e32 v27, v32, v32
	v_fmac_f32_e32 v27, v33, v33
	ds_write_b128 v35, v[22:25] offset:16
	v_add_f32_e32 v30, v34, v27
	ds_read_b128 v[22:25], v1 offset:64
	ds_read_b128 v[26:29], v1 offset:80
	v_lshlrev_b32_e32 v31, 16, v86
	s_waitcnt lgkmcnt(0)
	v_add_f32_e32 v22, v22, v31
	v_and_b32_e32 v31, 0xffff0000, v86
	v_add_f32_e32 v23, v23, v31
	v_cvt_pk_bf16_f32 v22, v22, v23
	v_lshlrev_b32_e32 v23, 16, v87
	v_add_f32_e32 v23, v24, v23
	v_and_b32_e32 v24, 0xffff0000, v87
	v_add_f32_e32 v24, v25, v24
	v_cvt_pk_bf16_f32 v23, v23, v24
	v_lshlrev_b32_e32 v24, 16, v88
	v_and_b32_e32 v25, 0xffff0000, v88
	v_add_f32_e32 v24, v26, v24
	v_add_f32_e32 v25, v27, v25
	v_cvt_pk_bf16_f32 v24, v24, v25
	v_lshlrev_b32_e32 v25, 16, v89
	v_and_b32_e32 v26, 0xffff0000, v89
	v_add_f32_e32 v25, v28, v25
	v_add_f32_e32 v26, v29, v26
	v_and_b32_e32 v27, 0xffff0000, v22
	v_cvt_pk_bf16_f32 v25, v25, v26
	v_lshlrev_b32_e32 v26, 16, v22
	v_mul_f32_e32 v27, v27, v27
	v_lshlrev_b32_e32 v28, 16, v23
	v_fmac_f32_e32 v27, v26, v26
	v_and_b32_e32 v29, 0xffff0000, v23
	v_fmac_f32_e32 v27, v28, v28
	v_lshlrev_b32_e32 v31, 16, v24
	v_fmac_f32_e32 v27, v29, v29
	v_and_b32_e32 v32, 0xffff0000, v24
	v_fmac_f32_e32 v27, v31, v31
	v_lshlrev_b32_e32 v33, 16, v25
	v_fmac_f32_e32 v27, v32, v32
	v_and_b32_e32 v34, 0xffff0000, v25
	v_fmac_f32_e32 v27, v33, v33
	v_fmac_f32_e32 v27, v34, v34
	ds_write_b128 v35, v[22:25] offset:32
	v_add_f32_e32 v30, v30, v27
	ds_read_b128 v[22:25], v1 offset:96
	ds_read_b128 v[26:29], v1 offset:112
	v_lshlrev_b32_e32 v31, 16, v70
	s_waitcnt lgkmcnt(0)
	v_add_f32_e32 v22, v22, v31
	v_and_b32_e32 v31, 0xffff0000, v70
	v_add_f32_e32 v23, v23, v31
	v_cvt_pk_bf16_f32 v22, v22, v23
	v_lshlrev_b32_e32 v23, 16, v71
	v_add_f32_e32 v23, v24, v23
	v_and_b32_e32 v24, 0xffff0000, v71
	v_add_f32_e32 v24, v25, v24
	v_cvt_pk_bf16_f32 v23, v23, v24
	v_lshlrev_b32_e32 v24, 16, v72
	v_and_b32_e32 v25, 0xffff0000, v72
	v_add_f32_e32 v24, v26, v24
	v_add_f32_e32 v25, v27, v25
	v_cvt_pk_bf16_f32 v24, v24, v25
	v_lshlrev_b32_e32 v25, 16, v73
	v_and_b32_e32 v26, 0xffff0000, v73
	v_add_f32_e32 v25, v28, v25
	v_add_f32_e32 v26, v29, v26
	v_and_b32_e32 v27, 0xffff0000, v22
	v_cvt_pk_bf16_f32 v25, v25, v26
	v_lshlrev_b32_e32 v26, 16, v22
	v_mul_f32_e32 v27, v27, v27
	v_lshlrev_b32_e32 v28, 16, v23
	v_fmac_f32_e32 v27, v26, v26
	v_and_b32_e32 v29, 0xffff0000, v23
	v_fmac_f32_e32 v27, v28, v28
	v_lshlrev_b32_e32 v31, 16, v24
	v_fmac_f32_e32 v27, v29, v29
	v_and_b32_e32 v32, 0xffff0000, v24
	v_fmac_f32_e32 v27, v31, v31
	v_lshlrev_b32_e32 v33, 16, v25
	v_fmac_f32_e32 v27, v32, v32
	v_and_b32_e32 v34, 0xffff0000, v25
	v_fmac_f32_e32 v27, v33, v33
	v_fmac_f32_e32 v27, v34, v34
	ds_write_b128 v35, v[22:25] offset:48
	v_add_f32_e32 v30, v30, v27
	ds_read_b128 v[22:25], v1 offset:128
	ds_read_b128 v[26:29], v1 offset:144
	v_lshlrev_b32_e32 v31, 16, v14
	v_and_b32_e32 v14, 0xffff0000, v14
	s_waitcnt lgkmcnt(0)
	v_add_f32_e32 v22, v22, v31
	v_add_f32_e32 v14, v23, v14
	v_cvt_pk_bf16_f32 v14, v22, v14
	v_lshlrev_b32_e32 v22, 16, v15
	v_and_b32_e32 v15, 0xffff0000, v15
	v_add_f32_e32 v22, v24, v22
	v_add_f32_e32 v15, v25, v15
	v_cvt_pk_bf16_f32 v15, v22, v15
	v_lshlrev_b32_e32 v22, 16, v16
	v_and_b32_e32 v16, 0xffff0000, v16
	v_add_f32_e32 v22, v26, v22
	v_add_f32_e32 v16, v27, v16
	v_cvt_pk_bf16_f32 v16, v22, v16
	v_lshlrev_b32_e32 v22, 16, v17
	v_and_b32_e32 v17, 0xffff0000, v17
	v_add_f32_e32 v22, v28, v22
	v_add_f32_e32 v17, v29, v17
	v_and_b32_e32 v23, 0xffff0000, v14
	v_cvt_pk_bf16_f32 v17, v22, v17
	v_lshlrev_b32_e32 v22, 16, v14
	v_mul_f32_e32 v23, v23, v23
	v_lshlrev_b32_e32 v24, 16, v15
	v_fmac_f32_e32 v23, v22, v22
	v_and_b32_e32 v25, 0xffff0000, v15
	v_fmac_f32_e32 v23, v24, v24
	v_lshlrev_b32_e32 v26, 16, v16
	v_fmac_f32_e32 v23, v25, v25
	v_and_b32_e32 v27, 0xffff0000, v16
	v_fmac_f32_e32 v23, v26, v26
	v_lshlrev_b32_e32 v28, 16, v17
	v_fmac_f32_e32 v23, v27, v27
	v_and_b32_e32 v29, 0xffff0000, v17
	v_fmac_f32_e32 v23, v28, v28
	v_fmac_f32_e32 v23, v29, v29
	ds_write_b128 v35, v[14:17] offset:64
	v_add_f32_e32 v26, v30, v23
	ds_read_b128 v[14:17], v1 offset:160
	ds_read_b128 v[22:25], v1 offset:176
	v_lshlrev_b32_e32 v27, 16, v10
	v_and_b32_e32 v10, 0xffff0000, v10
	s_waitcnt lgkmcnt(0)
	v_add_f32_e32 v14, v14, v27
	v_add_f32_e32 v10, v15, v10
	v_cvt_pk_bf16_f32 v10, v14, v10
	v_lshlrev_b32_e32 v14, 16, v11
	v_and_b32_e32 v11, 0xffff0000, v11
	v_add_f32_e32 v14, v16, v14
	v_add_f32_e32 v11, v17, v11
	v_cvt_pk_bf16_f32 v11, v14, v11
	v_lshlrev_b32_e32 v14, 16, v12
	v_and_b32_e32 v12, 0xffff0000, v12
	v_add_f32_e32 v14, v22, v14
	v_add_f32_e32 v12, v23, v12
	v_cvt_pk_bf16_f32 v12, v14, v12
	v_lshlrev_b32_e32 v14, 16, v13
	v_and_b32_e32 v13, 0xffff0000, v13
	v_add_f32_e32 v14, v24, v14
	v_add_f32_e32 v13, v25, v13
	v_and_b32_e32 v15, 0xffff0000, v10
	v_cvt_pk_bf16_f32 v13, v14, v13
	v_lshlrev_b32_e32 v14, 16, v10
	v_mul_f32_e32 v15, v15, v15
	v_lshlrev_b32_e32 v16, 16, v11
	v_fmac_f32_e32 v15, v14, v14
	v_and_b32_e32 v17, 0xffff0000, v11
	v_fmac_f32_e32 v15, v16, v16
	v_lshlrev_b32_e32 v22, 16, v12
	v_fmac_f32_e32 v15, v17, v17
	v_and_b32_e32 v23, 0xffff0000, v12
	v_fmac_f32_e32 v15, v22, v22
	v_lshlrev_b32_e32 v24, 16, v13
	v_fmac_f32_e32 v15, v23, v23
	v_and_b32_e32 v25, 0xffff0000, v13
	v_fmac_f32_e32 v15, v24, v24
	v_fmac_f32_e32 v15, v25, v25
	ds_write_b128 v35, v[10:13] offset:80
	v_add_f32_e32 v22, v26, v15
	ds_read_b128 v[10:13], v1 offset:192
	ds_read_b128 v[14:17], v1 offset:208
	v_lshlrev_b32_e32 v23, 16, v6
	v_and_b32_e32 v6, 0xffff0000, v6
	s_waitcnt lgkmcnt(0)
	v_add_f32_e32 v10, v10, v23
	v_add_f32_e32 v6, v11, v6
	v_cvt_pk_bf16_f32 v6, v10, v6
	v_lshlrev_b32_e32 v10, 16, v7
	v_and_b32_e32 v7, 0xffff0000, v7
	v_add_f32_e32 v10, v12, v10
	v_add_f32_e32 v7, v13, v7
	v_cvt_pk_bf16_f32 v7, v10, v7
	v_lshlrev_b32_e32 v10, 16, v8
	v_and_b32_e32 v8, 0xffff0000, v8
	v_add_f32_e32 v10, v14, v10
	v_add_f32_e32 v8, v15, v8
	v_cvt_pk_bf16_f32 v8, v10, v8
	v_lshlrev_b32_e32 v10, 16, v9
	v_and_b32_e32 v9, 0xffff0000, v9
	v_add_f32_e32 v10, v16, v10
	v_add_f32_e32 v9, v17, v9
	v_and_b32_e32 v11, 0xffff0000, v6
	v_cvt_pk_bf16_f32 v9, v10, v9
	v_lshlrev_b32_e32 v10, 16, v6
	v_mul_f32_e32 v11, v11, v11
	v_lshlrev_b32_e32 v12, 16, v7
	v_fmac_f32_e32 v11, v10, v10
	v_and_b32_e32 v13, 0xffff0000, v7
	v_fmac_f32_e32 v11, v12, v12
	v_lshlrev_b32_e32 v14, 16, v8
	v_fmac_f32_e32 v11, v13, v13
	v_and_b32_e32 v15, 0xffff0000, v8
	v_fmac_f32_e32 v11, v14, v14
	v_lshlrev_b32_e32 v16, 16, v9
	v_fmac_f32_e32 v11, v15, v15
	v_and_b32_e32 v17, 0xffff0000, v9
	v_fmac_f32_e32 v11, v16, v16
	v_fmac_f32_e32 v11, v17, v17
	ds_write_b128 v35, v[6:9] offset:96
	v_add_f32_e32 v14, v22, v11
	ds_read_b128 v[6:9], v1 offset:224
	ds_read_b128 v[10:13], v1 offset:240
	v_lshlrev_b32_e32 v1, 16, v2
	v_and_b32_e32 v2, 0xffff0000, v2
	s_waitcnt lgkmcnt(0)
	v_add_f32_e32 v1, v6, v1
	v_add_f32_e32 v2, v7, v2
	v_cvt_pk_bf16_f32 v2, v1, v2
	v_lshlrev_b32_e32 v1, 16, v3
	v_and_b32_e32 v3, 0xffff0000, v3
	v_add_f32_e32 v1, v8, v1
	v_add_f32_e32 v3, v9, v3
	v_cvt_pk_bf16_f32 v3, v1, v3
	v_lshlrev_b32_e32 v1, 16, v4
	v_and_b32_e32 v4, 0xffff0000, v4
	v_add_f32_e32 v1, v10, v1
	v_add_f32_e32 v4, v11, v4
	v_cvt_pk_bf16_f32 v4, v1, v4
	v_lshlrev_b32_e32 v1, 16, v5
	v_and_b32_e32 v5, 0xffff0000, v5
	v_add_f32_e32 v1, v12, v1
	v_add_f32_e32 v5, v13, v5
	v_and_b32_e32 v6, 0xffff0000, v2
	v_cvt_pk_bf16_f32 v5, v1, v5
	v_lshlrev_b32_e32 v1, 16, v2
	v_mul_f32_e32 v6, v6, v6
	v_lshlrev_b32_e32 v7, 16, v3
	v_fmac_f32_e32 v6, v1, v1
	v_and_b32_e32 v8, 0xffff0000, v3
	v_fmac_f32_e32 v6, v7, v7
	v_lshlrev_b32_e32 v9, 16, v4
	v_fmac_f32_e32 v6, v8, v8
	v_and_b32_e32 v10, 0xffff0000, v4
	v_fmac_f32_e32 v6, v9, v9
	v_lshlrev_b32_e32 v11, 16, v5
	v_fmac_f32_e32 v6, v10, v10
	v_and_b32_e32 v12, 0xffff0000, v5
	v_fmac_f32_e32 v6, v11, v11
	ds_write_b128 v35, v[2:5] offset:112
	v_and_b32_e32 v7, 63, v170
	v_lshrrev_b32_e32 v13, 3, v7
	v_sub_u32_e32 v13, v13, v7
	v_and_b32_e32 v7, 7, v7
	v_lshlrev_b32_e32 v7, 4, v7
	v_mul_i32_i24_e32 v2, 0x800, v13
	v_add_u32_e32 v2, v2, v7
	v_mul_i32_i24_e32 v13, 0x110, v13
	v_add3_u32 v13, v13, v7, v35
	s_waitcnt lgkmcnt(0)
	ds_read_b128 v[8:11], v13 offset:0
	v_mov_b32_e32 v4, v2
	v_ashrrev_i32_e32 v5, 31, v4
	v_lshl_add_u64 v[16:17], v[4:5], 0, v[20:21]
	s_waitcnt lgkmcnt(0)
	global_store_dwordx4 v[16:17], v[8:11], off offset:128
	ds_read_b128 v[24:27], v13 offset:2176
	v_add_u32_e32 v4, 0x4000, v2
	v_ashrrev_i32_e32 v5, 31, v4
	v_lshl_add_u64 v[16:17], v[4:5], 0, v[20:21]
	s_waitcnt lgkmcnt(0)
	global_store_dwordx4 v[16:17], v[24:27], off offset:128
	ds_read_b128 v[8:11], v13 offset:4352
	v_add_u32_e32 v4, 0x8000, v2
	v_ashrrev_i32_e32 v5, 31, v4
	v_lshl_add_u64 v[16:17], v[4:5], 0, v[20:21]
	s_waitcnt lgkmcnt(0)
	global_store_dwordx4 v[16:17], v[8:11], off offset:128
	ds_read_b128 v[24:27], v13 offset:6528
	v_add_u32_e32 v4, 0xc000, v2
	v_ashrrev_i32_e32 v5, 31, v4
	v_lshl_add_u64 v[16:17], v[4:5], 0, v[20:21]
	s_waitcnt lgkmcnt(0)
	global_store_dwordx4 v[16:17], v[24:27], off offset:128
	ds_read_b128 v[8:11], v13 offset:8704
	v_add_u32_e32 v4, 0x10000, v2
	v_ashrrev_i32_e32 v5, 31, v4
	v_lshl_add_u64 v[16:17], v[4:5], 0, v[20:21]
	s_waitcnt lgkmcnt(0)
	global_store_dwordx4 v[16:17], v[8:11], off offset:128
	ds_read_b128 v[24:27], v13 offset:10880
	v_add_u32_e32 v4, 0x14000, v2
	v_ashrrev_i32_e32 v5, 31, v4
	v_lshl_add_u64 v[16:17], v[4:5], 0, v[20:21]
	s_waitcnt lgkmcnt(0)
	global_store_dwordx4 v[16:17], v[24:27], off offset:128
	ds_read_b128 v[8:11], v13 offset:13056
	v_add_u32_e32 v4, 0x18000, v2
	v_ashrrev_i32_e32 v5, 31, v4
	v_lshl_add_u64 v[16:17], v[4:5], 0, v[20:21]
	s_waitcnt lgkmcnt(0)
	global_store_dwordx4 v[16:17], v[8:11], off offset:128
	ds_read_b128 v[24:27], v13 offset:15232
	v_add_u32_e32 v4, 0x1c000, v2
	v_ashrrev_i32_e32 v5, 31, v4
	v_lshl_add_u64 v[16:17], v[4:5], 0, v[20:21]
	s_waitcnt lgkmcnt(0)
	global_store_dwordx4 v[16:17], v[24:27], off offset:128
	v_fmac_f32_e32 v6, v12, v12
	v_add_f32_e32 v1, v14, v6
	v_lshlrev_b64 v[2:3], 6, v[18:19]
	v_lshl_add_u64 v[2:3], s[6:7], 0, v[2:3]
	v_lshl_add_u64 v[2:3], v[2:3], 0, s[18:19]
	flat_store_dword v[2:3], v1 offset:4
	s_branch .LBB0_342

.Lbk64_418:
	s_waitcnt vmcnt(4)
	ds_read_b128 v[192:195], v227
	ds_read_b128 v[196:199], v228
	ds_read_b128 v[200:203], v227 offset:2048
	ds_read_b128 v[204:207], v228 offset:2048
	ds_read_b128 v[208:211], v227 offset:4096
	ds_read_b128 v[212:215], v228 offset:4096
	ds_read_b128 v[216:219], v227 offset:6144
	ds_read_b128 v[220:223], v228 offset:6144
	s_waitcnt vmcnt(0)
	s_barrier
	s_add_u32 s4, s4, 0x80
	s_addc_u32 s5, s5, 0
	s_add_u32 s22, s22, 0x80
	s_addc_u32 s23, s23, 0
	s_waitcnt lgkmcnt(0)
	ds_read_b128 v[154:157], v229 offset:0
	ds_read_b128 v[158:161], v230 offset:0
	ds_read_b128 v[162:165], v229 offset:2048
	ds_read_b128 v[166:169], v230 offset:2048
	s_waitcnt lgkmcnt(2)
	v_mfma_f32_16x16x32_bf16 v[126:129], v[192:195], v[154:157], v[126:129]
	v_mfma_f32_16x16x32_bf16 v[114:117], v[200:203], v[154:157], v[114:117]
	v_mfma_f32_16x16x32_bf16 v[94:97], v[208:211], v[154:157], v[94:97]
	v_mfma_f32_16x16x32_bf16 v[62:65], v[216:219], v[154:157], v[62:65]
	v_readfirstlane_b32 s32, v142
	s_lshl_b32 m0, s32, 3
	v_add_u32_e32 v226, 0, v224
	v_max_i32_e32 v226, 0, v226
	v_min_i32_e32 v226, 0xffff, v226
	v_lshl_add_u32 v226, v226, 11, v231
	global_load_lds_dwordx4 v226, s[4:5]
	v_mfma_f32_16x16x32_bf16 v[126:129], v[196:199], v[158:161], v[126:129]
	v_mfma_f32_16x16x32_bf16 v[114:117], v[204:207], v[158:161], v[114:117]
	v_mfma_f32_16x16x32_bf16 v[94:97], v[212:215], v[158:161], v[94:97]
	v_mfma_f32_16x16x32_bf16 v[62:65], v[220:223], v[158:161], v[62:65]
	s_add_u32 m0, m0, 0x400
	v_add_u32_e32 v226, 8, v224
	v_max_i32_e32 v226, 0, v226
	v_min_i32_e32 v226, 0xffff, v226
	v_lshl_add_u32 v226, v226, 11, v231
	global_load_lds_dwordx4 v226, s[4:5]
	ds_read_b128 v[154:157], v229 offset:4096
	ds_read_b128 v[158:161], v230 offset:4096
	s_waitcnt lgkmcnt(2)
	v_mfma_f32_16x16x32_bf16 v[122:125], v[192:195], v[162:165], v[122:125]
	v_mfma_f32_16x16x32_bf16 v[106:109], v[200:203], v[162:165], v[106:109]
	v_mfma_f32_16x16x32_bf16 v[78:81], v[208:211], v[162:165], v[78:81]
	v_mfma_f32_16x16x32_bf16 v[46:49], v[216:219], v[162:165], v[46:49]
	s_add_u32 m0, m0, 0x400
	v_add_u32_e32 v226, 16, v224
	v_max_i32_e32 v226, 0, v226
	v_min_i32_e32 v226, 0xffff, v226
	v_lshl_add_u32 v226, v226, 11, v231
	global_load_lds_dwordx4 v226, s[4:5]
	v_mfma_f32_16x16x32_bf16 v[122:125], v[196:199], v[166:169], v[122:125]
	v_mfma_f32_16x16x32_bf16 v[106:109], v[204:207], v[166:169], v[106:109]
	v_mfma_f32_16x16x32_bf16 v[78:81], v[212:215], v[166:169], v[78:81]
	v_mfma_f32_16x16x32_bf16 v[46:49], v[220:223], v[166:169], v[46:49]
	s_add_u32 m0, m0, 0x400
	v_add_u32_e32 v226, 24, v224
	v_max_i32_e32 v226, 0, v226
	v_min_i32_e32 v226, 0xffff, v226
	v_lshl_add_u32 v226, v226, 11, v231
	global_load_lds_dwordx4 v226, s[4:5]
	ds_read_b128 v[162:165], v229 offset:6144
	ds_read_b128 v[166:169], v230 offset:6144
	s_waitcnt lgkmcnt(2)
	v_mfma_f32_16x16x32_bf16 v[118:121], v[192:195], v[154:157], v[118:121]
	v_mfma_f32_16x16x32_bf16 v[98:101], v[200:203], v[154:157], v[98:101]
	v_mfma_f32_16x16x32_bf16 v[70:73], v[208:211], v[154:157], v[70:73]
	v_mfma_f32_16x16x32_bf16 v[38:41], v[216:219], v[154:157], v[38:41]
	s_add_u32 m0, m0, 0x400
	v_add_u32_e32 v226, 32, v224
	v_max_i32_e32 v226, 0, v226
	v_min_i32_e32 v226, 0xffff, v226
	v_lshl_add_u32 v226, v226, 11, v231
	global_load_lds_dwordx4 v226, s[4:5]
	v_mfma_f32_16x16x32_bf16 v[118:121], v[196:199], v[158:161], v[118:121]
	v_mfma_f32_16x16x32_bf16 v[98:101], v[204:207], v[158:161], v[98:101]
	v_mfma_f32_16x16x32_bf16 v[70:73], v[212:215], v[158:161], v[70:73]
	v_mfma_f32_16x16x32_bf16 v[38:41], v[220:223], v[158:161], v[38:41]
	s_add_u32 m0, m0, 0x400
	v_add_u32_e32 v226, 40, v224
	v_max_i32_e32 v226, 0, v226
	v_min_i32_e32 v226, 0xffff, v226
	v_lshl_add_u32 v226, v226, 11, v231
	global_load_lds_dwordx4 v226, s[4:5]
	ds_read_b128 v[154:157], v229 offset:8192
	ds_read_b128 v[158:161], v230 offset:8192
	s_waitcnt lgkmcnt(2)
	v_mfma_f32_16x16x32_bf16 v[110:113], v[192:195], v[162:165], v[110:113]
	v_mfma_f32_16x16x32_bf16 v[86:89], v[200:203], v[162:165], v[86:89]
	v_mfma_f32_16x16x32_bf16 v[54:57], v[208:211], v[162:165], v[54:57]
	v_mfma_f32_16x16x32_bf16 v[26:29], v[216:219], v[162:165], v[26:29]
	s_add_u32 m0, m0, 0x400
	v_add_u32_e32 v226, 48, v224
	v_max_i32_e32 v226, 0, v226
	v_min_i32_e32 v226, 0xffff, v226
	v_lshl_add_u32 v226, v226, 11, v231
	global_load_lds_dwordx4 v226, s[4:5]
	v_mfma_f32_16x16x32_bf16 v[110:113], v[196:199], v[166:169], v[110:113]
	v_mfma_f32_16x16x32_bf16 v[86:89], v[204:207], v[166:169], v[86:89]
	v_mfma_f32_16x16x32_bf16 v[54:57], v[212:215], v[166:169], v[54:57]
	v_mfma_f32_16x16x32_bf16 v[26:29], v[220:223], v[166:169], v[26:29]
	s_add_u32 m0, m0, 0x400
	v_add_u32_e32 v226, 56, v224
	v_max_i32_e32 v226, 0, v226
	v_min_i32_e32 v226, 0xffff, v226
	v_lshl_add_u32 v226, v226, 11, v231
	global_load_lds_dwordx4 v226, s[4:5]
	ds_read_b128 v[162:165], v229 offset:10240
	ds_read_b128 v[166:169], v230 offset:10240
	s_waitcnt lgkmcnt(2)
	v_mfma_f32_16x16x32_bf16 v[102:105], v[192:195], v[154:157], v[102:105]
	v_mfma_f32_16x16x32_bf16 v[74:77], v[200:203], v[154:157], v[74:77]
	v_mfma_f32_16x16x32_bf16 v[42:45], v[208:211], v[154:157], v[42:45]
	v_mfma_f32_16x16x32_bf16 v[18:21], v[216:219], v[154:157], v[18:21]
	s_add_u32 m0, s21, 17
	s_and_b32 m0, m0, 1
	s_lshl_b32 m0, m0, 14
	s_add_u32 m0, m0, 0x8000
	v_readfirstlane_b32 s32, v142
	s_lshl_b32 s32, s32, 2
	s_add_u32 m0, m0, s32
	v_mov_b32_e32 v226, v225
	global_load_lds_dwordx4 v226, s[22:23]
	v_mfma_f32_16x16x32_bf16 v[102:105], v[196:199], v[158:161], v[102:105]
	v_mfma_f32_16x16x32_bf16 v[74:77], v[204:207], v[158:161], v[74:77]
	v_mfma_f32_16x16x32_bf16 v[42:45], v[212:215], v[158:161], v[42:45]
	v_mfma_f32_16x16x32_bf16 v[18:21], v[220:223], v[158:161], v[18:21]
	s_add_u32 m0, m0, 0x400
	v_add_u32_e32 v226, 0x4000, v225
	global_load_lds_dwordx4 v226, s[22:23]
	ds_read_b128 v[154:157], v229 offset:12288
	ds_read_b128 v[158:161], v230 offset:12288
	s_waitcnt lgkmcnt(2)
	v_mfma_f32_16x16x32_bf16 v[90:93], v[192:195], v[162:165], v[90:93]
	v_mfma_f32_16x16x32_bf16 v[58:61], v[200:203], v[162:165], v[58:61]
	v_mfma_f32_16x16x32_bf16 v[30:33], v[208:211], v[162:165], v[30:33]
	v_mfma_f32_16x16x32_bf16 v[10:13], v[216:219], v[162:165], v[10:13]
	s_add_u32 m0, m0, 0x400
	v_add_u32_e32 v226, 0x8000, v225
	global_load_lds_dwordx4 v226, s[22:23]
	v_mfma_f32_16x16x32_bf16 v[90:93], v[196:199], v[166:169], v[90:93]
	v_mfma_f32_16x16x32_bf16 v[58:61], v[204:207], v[166:169], v[58:61]
	v_mfma_f32_16x16x32_bf16 v[30:33], v[212:215], v[166:169], v[30:33]
	v_mfma_f32_16x16x32_bf16 v[10:13], v[220:223], v[166:169], v[10:13]
	s_add_u32 m0, m0, 0x400
	v_add_u32_e32 v226, 0xc000, v225
	global_load_lds_dwordx4 v226, s[22:23]
	ds_read_b128 v[162:165], v229 offset:14336
	ds_read_b128 v[166:169], v230 offset:14336
	s_waitcnt lgkmcnt(2)
	v_mfma_f32_16x16x32_bf16 v[82:85], v[192:195], v[154:157], v[82:85]
	v_mfma_f32_16x16x32_bf16 v[50:53], v[200:203], v[154:157], v[50:53]
	v_mfma_f32_16x16x32_bf16 v[22:25], v[208:211], v[154:157], v[22:25]
	v_mfma_f32_16x16x32_bf16 v[6:9], v[216:219], v[154:157], v[6:9]
	v_mfma_f32_16x16x32_bf16 v[82:85], v[196:199], v[158:161], v[82:85]
	v_mfma_f32_16x16x32_bf16 v[50:53], v[204:207], v[158:161], v[50:53]
	v_mfma_f32_16x16x32_bf16 v[22:25], v[212:215], v[158:161], v[22:25]
	v_mfma_f32_16x16x32_bf16 v[6:9], v[220:223], v[158:161], v[6:9]
	s_waitcnt lgkmcnt(0)
	v_mfma_f32_16x16x32_bf16 v[66:69], v[192:195], v[162:165], v[66:69]
	v_mfma_f32_16x16x32_bf16 v[34:37], v[200:203], v[162:165], v[34:37]
	v_mfma_f32_16x16x32_bf16 v[14:17], v[208:211], v[162:165], v[14:17]
	v_mfma_f32_16x16x32_bf16 v[2:5], v[216:219], v[162:165], v[2:5]
	v_mfma_f32_16x16x32_bf16 v[66:69], v[196:199], v[166:169], v[66:69]
	v_mfma_f32_16x16x32_bf16 v[34:37], v[204:207], v[166:169], v[34:37]
	v_mfma_f32_16x16x32_bf16 v[14:17], v[212:215], v[166:169], v[14:17]
	v_mfma_f32_16x16x32_bf16 v[2:5], v[220:223], v[166:169], v[2:5]
	v_xor_b32_e32 v229, 0x4000, v229
	v_xor_b32_e32 v230, 0x4000, v230
	s_add_i32 s21, s21, 1
	s_cmp_lg_u32 s21, 15
	s_cbranch_scc1 .Lbk64_418
	s_waitcnt vmcnt(4)
	ds_read_b128 v[192:195], v227
	ds_read_b128 v[196:199], v228
	ds_read_b128 v[200:203], v227 offset:2048
	ds_read_b128 v[204:207], v228 offset:2048
	ds_read_b128 v[208:211], v227 offset:4096
	ds_read_b128 v[212:215], v228 offset:4096
	ds_read_b128 v[216:219], v227 offset:6144
	ds_read_b128 v[220:223], v228 offset:6144
	s_waitcnt vmcnt(0)
	s_barrier
	s_waitcnt lgkmcnt(0)
	ds_read_b128 v[154:157], v229 offset:0
	ds_read_b128 v[158:161], v230 offset:0
	ds_read_b128 v[162:165], v229 offset:2048
	ds_read_b128 v[166:169], v230 offset:2048
	s_waitcnt lgkmcnt(2)
	v_mfma_f32_16x16x32_bf16 v[126:129], v[192:195], v[154:157], v[126:129]
	v_mfma_f32_16x16x32_bf16 v[114:117], v[200:203], v[154:157], v[114:117]
	v_mfma_f32_16x16x32_bf16 v[94:97], v[208:211], v[154:157], v[94:97]
	v_mfma_f32_16x16x32_bf16 v[62:65], v[216:219], v[154:157], v[62:65]
	v_mfma_f32_16x16x32_bf16 v[126:129], v[196:199], v[158:161], v[126:129]
	v_mfma_f32_16x16x32_bf16 v[114:117], v[204:207], v[158:161], v[114:117]
	v_mfma_f32_16x16x32_bf16 v[94:97], v[212:215], v[158:161], v[94:97]
	v_mfma_f32_16x16x32_bf16 v[62:65], v[220:223], v[158:161], v[62:65]
	ds_read_b128 v[154:157], v229 offset:4096
	ds_read_b128 v[158:161], v230 offset:4096
	s_waitcnt lgkmcnt(2)
	v_mfma_f32_16x16x32_bf16 v[122:125], v[192:195], v[162:165], v[122:125]
	v_mfma_f32_16x16x32_bf16 v[106:109], v[200:203], v[162:165], v[106:109]
	v_mfma_f32_16x16x32_bf16 v[78:81], v[208:211], v[162:165], v[78:81]
	v_mfma_f32_16x16x32_bf16 v[46:49], v[216:219], v[162:165], v[46:49]
	v_mfma_f32_16x16x32_bf16 v[122:125], v[196:199], v[166:169], v[122:125]
	v_mfma_f32_16x16x32_bf16 v[106:109], v[204:207], v[166:169], v[106:109]
	v_mfma_f32_16x16x32_bf16 v[78:81], v[212:215], v[166:169], v[78:81]
	v_mfma_f32_16x16x32_bf16 v[46:49], v[220:223], v[166:169], v[46:49]
	ds_read_b128 v[162:165], v229 offset:6144
	ds_read_b128 v[166:169], v230 offset:6144
	s_waitcnt lgkmcnt(2)
	v_mfma_f32_16x16x32_bf16 v[118:121], v[192:195], v[154:157], v[118:121]
	v_mfma_f32_16x16x32_bf16 v[98:101], v[200:203], v[154:157], v[98:101]
	v_mfma_f32_16x16x32_bf16 v[70:73], v[208:211], v[154:157], v[70:73]
	v_mfma_f32_16x16x32_bf16 v[38:41], v[216:219], v[154:157], v[38:41]
	v_mfma_f32_16x16x32_bf16 v[118:121], v[196:199], v[158:161], v[118:121]
	v_mfma_f32_16x16x32_bf16 v[98:101], v[204:207], v[158:161], v[98:101]
	v_mfma_f32_16x16x32_bf16 v[70:73], v[212:215], v[158:161], v[70:73]
	v_mfma_f32_16x16x32_bf16 v[38:41], v[220:223], v[158:161], v[38:41]
	ds_read_b128 v[154:157], v229 offset:8192
	ds_read_b128 v[158:161], v230 offset:8192
	s_waitcnt lgkmcnt(2)
	v_mfma_f32_16x16x32_bf16 v[110:113], v[192:195], v[162:165], v[110:113]
	v_mfma_f32_16x16x32_bf16 v[86:89], v[200:203], v[162:165], v[86:89]
	v_mfma_f32_16x16x32_bf16 v[54:57], v[208:211], v[162:165], v[54:57]
	v_mfma_f32_16x16x32_bf16 v[26:29], v[216:219], v[162:165], v[26:29]
	v_mfma_f32_16x16x32_bf16 v[110:113], v[196:199], v[166:169], v[110:113]
	v_mfma_f32_16x16x32_bf16 v[86:89], v[204:207], v[166:169], v[86:89]
	v_mfma_f32_16x16x32_bf16 v[54:57], v[212:215], v[166:169], v[54:57]
	v_mfma_f32_16x16x32_bf16 v[26:29], v[220:223], v[166:169], v[26:29]
	ds_read_b128 v[162:165], v229 offset:10240
	ds_read_b128 v[166:169], v230 offset:10240
	s_waitcnt lgkmcnt(2)
	v_mfma_f32_16x16x32_bf16 v[102:105], v[192:195], v[154:157], v[102:105]
	v_mfma_f32_16x16x32_bf16 v[74:77], v[200:203], v[154:157], v[74:77]
	v_mfma_f32_16x16x32_bf16 v[42:45], v[208:211], v[154:157], v[42:45]
	v_mfma_f32_16x16x32_bf16 v[18:21], v[216:219], v[154:157], v[18:21]
	v_mfma_f32_16x16x32_bf16 v[102:105], v[196:199], v[158:161], v[102:105]
	v_mfma_f32_16x16x32_bf16 v[74:77], v[204:207], v[158:161], v[74:77]
	v_mfma_f32_16x16x32_bf16 v[42:45], v[212:215], v[158:161], v[42:45]
	v_mfma_f32_16x16x32_bf16 v[18:21], v[220:223], v[158:161], v[18:21]
	ds_read_b128 v[154:157], v229 offset:12288
	ds_read_b128 v[158:161], v230 offset:12288
	s_waitcnt lgkmcnt(2)
	v_mfma_f32_16x16x32_bf16 v[90:93], v[192:195], v[162:165], v[90:93]
	v_mfma_f32_16x16x32_bf16 v[58:61], v[200:203], v[162:165], v[58:61]
	v_mfma_f32_16x16x32_bf16 v[30:33], v[208:211], v[162:165], v[30:33]
	v_mfma_f32_16x16x32_bf16 v[10:13], v[216:219], v[162:165], v[10:13]
	v_mfma_f32_16x16x32_bf16 v[90:93], v[196:199], v[166:169], v[90:93]
	v_mfma_f32_16x16x32_bf16 v[58:61], v[204:207], v[166:169], v[58:61]
	v_mfma_f32_16x16x32_bf16 v[30:33], v[212:215], v[166:169], v[30:33]
	v_mfma_f32_16x16x32_bf16 v[10:13], v[220:223], v[166:169], v[10:13]
	ds_read_b128 v[162:165], v229 offset:14336
	ds_read_b128 v[166:169], v230 offset:14336
	s_waitcnt lgkmcnt(2)
	v_mfma_f32_16x16x32_bf16 v[82:85], v[192:195], v[154:157], v[82:85]
	v_mfma_f32_16x16x32_bf16 v[50:53], v[200:203], v[154:157], v[50:53]
	v_mfma_f32_16x16x32_bf16 v[22:25], v[208:211], v[154:157], v[22:25]
	v_mfma_f32_16x16x32_bf16 v[6:9], v[216:219], v[154:157], v[6:9]
	v_mfma_f32_16x16x32_bf16 v[82:85], v[196:199], v[158:161], v[82:85]
	v_mfma_f32_16x16x32_bf16 v[50:53], v[204:207], v[158:161], v[50:53]
	v_mfma_f32_16x16x32_bf16 v[22:25], v[212:215], v[158:161], v[22:25]
	v_mfma_f32_16x16x32_bf16 v[6:9], v[220:223], v[158:161], v[6:9]
	s_waitcnt lgkmcnt(0)
	v_mfma_f32_16x16x32_bf16 v[66:69], v[192:195], v[162:165], v[66:69]
	v_mfma_f32_16x16x32_bf16 v[34:37], v[200:203], v[162:165], v[34:37]
	v_mfma_f32_16x16x32_bf16 v[14:17], v[208:211], v[162:165], v[14:17]
	v_mfma_f32_16x16x32_bf16 v[2:5], v[216:219], v[162:165], v[2:5]
	v_mfma_f32_16x16x32_bf16 v[66:69], v[196:199], v[166:169], v[66:69]
	v_mfma_f32_16x16x32_bf16 v[34:37], v[204:207], v[166:169], v[34:37]
	v_mfma_f32_16x16x32_bf16 v[14:17], v[212:215], v[166:169], v[14:17]
	v_mfma_f32_16x16x32_bf16 v[2:5], v[220:223], v[166:169], v[2:5]
	s_nop 7
	s_nop 7
	s_waitcnt vmcnt(6)
	v_add_u32_e32 v142, v149, v147
	s_waitcnt lgkmcnt(0)
	v_and_b32_e32 v1, 0xfffffc0, v1
	v_lshl_or_b32 v1, v144, 2, v1
	v_mul_lo_u32 v1, v1, s33
	v_lshl_or_b32 v1, v143, 2, v1
	s_waitcnt lgkmcnt(0)
	s_waitcnt lgkmcnt(0)
	s_waitcnt lgkmcnt(0)
	s_waitcnt lgkmcnt(0)
	s_waitcnt lgkmcnt(0)
	v_mov_b64_e32 v[162:163], v[30:31]
	v_mov_b64_e32 v[164:165], v[32:33]
	v_mov_b64_e32 v[134:135], v[10:11]
	v_mov_b64_e32 v[136:137], v[12:13]
	s_nop 2
	s_waitcnt lgkmcnt(0)
	v_mov_b64_e32 v[180:181], v[6:7]
	v_mov_b64_e32 v[182:183], v[8:9]
	s_nop 2
	s_waitcnt vmcnt(0)
	v_mov_b64_e32 v[166:167], v[22:23]
	v_mov_b64_e32 v[168:169], v[24:25]
	s_waitcnt lgkmcnt(0)
	v_mov_b64_e32 v[130:131], v[34:35]
	v_mov_b64_e32 v[132:133], v[36:37]
	v_mov_b64_e32 v[138:139], v[14:15]
	v_mov_b64_e32 v[140:141], v[16:17]
	v_mov_b64_e32 v[158:159], v[2:3]
	v_mov_b64_e32 v[160:161], v[4:5]
	s_nop 1
	s_waitcnt lgkmcnt(0)
	v_mov_b64_e32 v[22:23], v[126:127]
	v_mov_b64_e32 v[24:25], v[128:129]
	s_nop 2
	v_mov_b64_e32 v[32:33], v[114:115]
	v_mov_b64_e32 v[34:35], v[116:117]
	s_nop 2
	s_waitcnt lgkmcnt(0)
	v_mov_b64_e32 v[2:3], v[122:123]
	v_mov_b64_e32 v[4:5], v[124:125]
	v_mov_b64_e32 v[122:123], v[46:47]
	v_mov_b64_e32 v[124:125], v[48:49]
	s_waitcnt lgkmcnt(0)
	v_mov_b64_e32 v[46:47], v[118:119]
	v_mov_b64_e32 v[48:49], v[120:121]
	v_mov_b64_e32 v[118:119], v[38:39]
	v_mov_b64_e32 v[120:121], v[40:41]
	v_mov_b64_e32 v[36:37], v[110:111]
	v_mov_b64_e32 v[38:39], v[112:113]
	s_nop 2
	s_waitcnt vmcnt(0) lgkmcnt(0)
	s_barrier
	ds_write2_b32 v1, v22, v2 offset1:16
	ds_write2_b32 v1, v23, v3 offset0:68 offset1:84
	ds_write2_b32 v1, v24, v4 offset0:136 offset1:152
	ds_write2_b32 v1, v25, v5 offset0:204 offset1:220
	ds_write2_b32 v1, v46, v36 offset0:32 offset1:48
	ds_write2_b32 v1, v47, v37 offset0:100 offset1:116
	ds_write2_b32 v1, v48, v38 offset0:168 offset1:184
	ds_write2_b32 v1, v49, v39 offset0:236 offset1:252
	v_mov_b64_e32 v[200:201], v[86:87]
	v_mov_b64_e32 v[202:203], v[88:89]
	s_nop 1
	v_add_u32_e32 v88, 0x1000, v1
	ds_write2_b32 v88, v32, v106 offset0:64 offset1:80
	ds_write2_b32 v88, v33, v107 offset0:132 offset1:148
	ds_write2_b32 v88, v34, v108 offset0:200 offset1:216
	v_add_u32_e32 v89, 0x1400, v1
	v_mov_b64_e32 v[212:213], v[26:27]
	v_mov_b64_e32 v[214:215], v[28:29]
	ds_write2_b32 v89, v35, v109 offset0:12 offset1:28
	ds_write2_b32 v88, v98, v200 offset0:96 offset1:112
	ds_write2_b32 v88, v99, v201 offset0:164 offset1:180
	ds_write2_b32 v88, v100, v202 offset0:232 offset1:248
	ds_write2_b32 v89, v101, v203 offset0:44 offset1:60
	v_mov_b64_e32 v[30:31], v[90:91]
	v_mov_b64_e32 v[32:33], v[92:93]
	s_nop 2
	v_add_u32_e32 v90, 0x2000, v1
	v_add_u32_e32 v91, 0x2400, v1
	ds_write2_b32 v90, v94, v78 offset0:128 offset1:144
	ds_write2_b32 v90, v95, v79 offset0:196 offset1:212
	ds_write2_b32 v91, v96, v80 offset0:8 offset1:24
	ds_write2_b32 v91, v97, v81 offset0:76 offset1:92
	ds_write2_b32 v90, v70, v54 offset0:160 offset1:176
	ds_write2_b32 v90, v71, v55 offset0:228 offset1:244
	ds_write2_b32 v91, v72, v56 offset0:40 offset1:56
	v_add_u32_e32 v92, 0x3000, v1
	v_add_u32_e32 v93, 0x3400, v1
	v_mov_b32_e32 v70, v170
	v_mov_b64_e32 v[6:7], v[42:43]
	v_mov_b64_e32 v[8:9], v[44:45]
	ds_write2_b32 v91, v73, v57 offset0:108 offset1:124
	ds_write2_b32 v92, v62, v122 offset0:192 offset1:208
	ds_write2_b32 v93, v63, v123 offset0:4 offset1:20
	ds_write2_b32 v93, v64, v124 offset0:72 offset1:88
	v_mov_b64_e32 v[42:43], v[50:51]
	v_mov_b64_e32 v[44:45], v[52:53]
	ds_write2_b32 v93, v65, v125 offset0:140 offset1:156
	ds_write2_b32 v92, v118, v212 offset0:224 offset1:240
	ds_write2_b32 v93, v119, v213 offset0:36 offset1:52
	ds_write2_b32 v93, v120, v214 offset0:104 offset1:120
	ds_write2_b32 v93, v121, v215 offset0:172 offset1:188
	s_waitcnt lgkmcnt(0)
	s_barrier
	v_mov_b64_e32 v[14:15], v[102:103]
	v_mov_b64_e32 v[16:17], v[104:105]
	v_ashrrev_i32_e32 v50, 7, v70
	v_mov_b64_e32 v[10:11], v[74:75]
	v_mov_b64_e32 v[12:13], v[76:77]
	v_mov_b64_e32 v[2:3], v[18:19]
	v_mov_b64_e32 v[4:5], v[20:21]
	v_mov_b64_e32 v[26:27], v[58:59]
	v_mov_b64_e32 v[28:29], v[60:61]
	v_mov_b64_e32 v[22:23], v[162:163]
	v_mov_b64_e32 v[24:25], v[164:165]
	v_mov_b64_e32 v[18:19], v[134:135]
	v_mov_b64_e32 v[20:21], v[136:137]
	v_mov_b64_e32 v[46:47], v[82:83]
	v_mov_b64_e32 v[48:49], v[84:85]
	v_mov_b64_e32 v[38:39], v[166:167]
	v_mov_b64_e32 v[40:41], v[168:169]
	v_mov_b64_e32 v[34:35], v[180:181]
	v_mov_b64_e32 v[36:37], v[182:183]
	v_mov_b64_e32 v[62:63], v[66:67]
	v_mov_b64_e32 v[64:65], v[68:69]
	v_mov_b64_e32 v[58:59], v[130:131]
	v_mov_b64_e32 v[60:61], v[132:133]
	s_nop 1
	v_add_u32_e32 v66, s46, v50
	v_cmp_lt_i32_e32 vcc, s91, v66
	v_mov_b64_e32 v[54:55], v[138:139]
	v_mov_b64_e32 v[56:57], v[140:141]
	v_mov_b64_e32 v[50:51], v[158:159]
	v_mov_b64_e32 v[52:53], v[160:161]
	s_and_saveexec_b64 s[4:5], vcc
	s_xor_b64 s[22:23], exec, s[4:5]
	v_add_u32_e32 v66, 0xfffffef0, v66
	v_mul_hi_u32 v67, v66, s96
	v_lshrrev_b32_e32 v67, 3, v67
	v_add_u32_e32 v68, 16, v67
	v_lshl_add_u32 v67, v67, 5, v67
	v_sub_u32_e32 v71, v66, v67
	s_or_saveexec_b64 s[22:23], s[22:23]
	v_mov_b32_e32 v72, 0x1000
	s_xor_b64 exec, exec, s[22:23]
	v_mul_hi_i32 v67, v66, s97
	v_lshrrev_b32_e32 v68, 31, v67
	v_ashrrev_i32_e32 v67, 3, v67
	v_add_u32_e32 v68, v67, v68
	v_lshl_add_u32 v67, v68, 4, v68
	v_sub_u32_e32 v71, v66, v67
	v_mov_b32_e32 v72, 0x800
	s_or_b64 exec, exec, s[22:23]
	v_cmp_lt_i32_e32 vcc, 15, v68
	s_and_saveexec_b64 s[4:5], vcc
	s_xor_b64 s[4:5], exec, s[4:5]
	v_add_u32_e32 v66, -16, v68
	v_mov_b32_e32 v67, v0
	v_lshlrev_b64 v[66:67], 12, v[66:67]
	v_lshl_add_u64 v[66:67], v[66:67], 0, s[42:43]
	s_andn2_saveexec_b64 s[22:23], s[4:5]
	v_ashrrev_i32_e32 v69, 31, v68
	v_lshlrev_b64 v[66:67], 11, v[68:69]
	s_or_b64 exec, exec, s[22:23]
	v_and_b32_e32 v69, 0x7f, v70
	v_cmp_gt_i32_e32 vcc, s79, v69
	s_and_saveexec_b64 s[22:23], vcc
	s_cbranch_execz .LBB0_436
	v_cmp_ne_u32_e32 vcc, 0, v69
	s_and_b64 exec, exec, vcc
	s_cbranch_execz .LBB0_436
	v_mul_lo_u32 v71, v71, s54
	v_add3_u32 v68, v69, v71, -1
	v_cmp_lt_i32_e32 vcc, v68, v72
	s_and_b64 exec, exec, vcc
	s_cbranch_execz .LBB0_436
	v_cmp_lt_i32_e32 vcc, 0, v68
	v_mov_b32_e32 v83, 0
	v_mov_b32_e32 v82, 0
	s_and_saveexec_b64 s[4:5], vcc
	v_mov_b32_e32 v73, 0x11ffc
	v_lshl_add_u32 v73, v70, 2, v73
	ds_read_b32 v82, v73
	s_or_b64 exec, exec, s[4:5]
	v_add_u32_e32 v69, v71, v69
	v_cmp_lt_i32_e32 vcc, v69, v72
	v_lshl_add_u32 v69, v70, 2, v175
	ds_read_b32 v84, v69
	s_and_saveexec_b64 s[4:5], vcc
	ds_read_b32 v83, v69 offset:4
	s_or_b64 exec, exec, s[4:5]
	s_lshl_b32 s4, s20, 6
	s_ashr_i32 s5, s4, 31
	s_lshl_b64 s[4:5], s[4:5], 1
	v_ashrrev_i32_e32 v69, 31, v68
	s_add_u32 s4, s38, s4
	v_lshl_add_u64 v[66:67], v[66:67], 0, v[68:69]
	v_mul_lo_u32 v68, v70, s33
	s_addc_u32 s5, s39, s5
	v_add_u32_e32 v94, 0xfffffef0, v68
	v_mov_b64_e32 v[68:69], s[4:5]
	v_mad_u64_u32 v[86:87], s[4:5], v66, s3, v[68:69]
	v_mov_b32_e32 v66, v87
	v_mad_u64_u32 v[66:67], s[4:5], v67, s3, v[66:67]
	v_mov_b32_e32 v87, v66
	s_mov_b32 s4, 0
	v_add_u32_e32 v251, 0x190, v94

.Lbk64_530:
	s_waitcnt vmcnt(4)
	ds_read_b128 v[192:195], v227
	ds_read_b128 v[196:199], v228
	ds_read_b128 v[200:203], v227 offset:2048
	ds_read_b128 v[204:207], v228 offset:2048
	ds_read_b128 v[208:211], v227 offset:4096
	ds_read_b128 v[212:215], v228 offset:4096
	ds_read_b128 v[216:219], v227 offset:6144
	ds_read_b128 v[220:223], v228 offset:6144
	s_waitcnt vmcnt(0)
	s_barrier
	s_add_u32 s18, s18, 0x80
	s_addc_u32 s19, s19, 0
	s_waitcnt lgkmcnt(0)
	ds_read_b128 v[154:157], v229 offset:0
	ds_read_b128 v[158:161], v230 offset:0
	ds_read_b128 v[162:165], v229 offset:2048
	ds_read_b128 v[166:169], v230 offset:2048
	s_waitcnt lgkmcnt(2)
	v_mfma_f32_16x16x32_bf16 v[126:129], v[192:195], v[154:157], v[126:129]
	v_mfma_f32_16x16x32_bf16 v[114:117], v[200:203], v[154:157], v[114:117]
	v_mfma_f32_16x16x32_bf16 v[86:89], v[208:211], v[154:157], v[86:89]
	v_mfma_f32_16x16x32_bf16 v[54:57], v[216:219], v[154:157], v[54:57]
	v_readfirstlane_b32 s32, v145
	s_lshl_b32 m0, s32, 3
	v_mov_b32_e32 v226, v224
	global_load_lds_dwordx4 v226, s[18:19]
	v_mfma_f32_16x16x32_bf16 v[126:129], v[196:199], v[158:161], v[126:129]
	v_mfma_f32_16x16x32_bf16 v[114:117], v[204:207], v[158:161], v[114:117]
	v_mfma_f32_16x16x32_bf16 v[86:89], v[212:215], v[158:161], v[86:89]
	v_mfma_f32_16x16x32_bf16 v[54:57], v[220:223], v[158:161], v[54:57]
	s_add_u32 m0, m0, 0x400
	v_add_u32_e32 v226, 0x4000, v224
	global_load_lds_dwordx4 v226, s[18:19]
	ds_read_b128 v[154:157], v229 offset:4096
	ds_read_b128 v[158:161], v230 offset:4096
	s_waitcnt lgkmcnt(2)
	v_mfma_f32_16x16x32_bf16 v[122:125], v[192:195], v[162:165], v[122:125]
	v_mfma_f32_16x16x32_bf16 v[102:105], v[200:203], v[162:165], v[102:105]
	v_mfma_f32_16x16x32_bf16 v[70:73], v[208:211], v[162:165], v[70:73]
	v_mfma_f32_16x16x32_bf16 v[38:41], v[216:219], v[162:165], v[38:41]
	s_add_u32 m0, m0, 0x400
	v_add_u32_e32 v226, 0x8000, v224
	global_load_lds_dwordx4 v226, s[18:19]
	v_mfma_f32_16x16x32_bf16 v[122:125], v[196:199], v[166:169], v[122:125]
	v_mfma_f32_16x16x32_bf16 v[102:105], v[204:207], v[166:169], v[102:105]
	v_mfma_f32_16x16x32_bf16 v[70:73], v[212:215], v[166:169], v[70:73]
	v_mfma_f32_16x16x32_bf16 v[38:41], v[220:223], v[166:169], v[38:41]
	s_add_u32 m0, m0, 0x400
	v_add_u32_e32 v226, 0xc000, v224
	global_load_lds_dwordx4 v226, s[18:19]
	ds_read_b128 v[162:165], v229 offset:6144
	ds_read_b128 v[166:169], v230 offset:6144
	s_waitcnt lgkmcnt(2)
	v_mfma_f32_16x16x32_bf16 v[118:121], v[192:195], v[154:157], v[118:121]
	v_mfma_f32_16x16x32_bf16 v[90:93], v[200:203], v[154:157], v[90:93]
	v_mfma_f32_16x16x32_bf16 v[58:61], v[208:211], v[154:157], v[58:61]
	v_mfma_f32_16x16x32_bf16 v[26:29], v[216:219], v[154:157], v[26:29]
	s_add_u32 m0, m0, 0x400
	v_add_u32_e32 v226, 0x10000, v224
	global_load_lds_dwordx4 v226, s[18:19]
	v_mfma_f32_16x16x32_bf16 v[118:121], v[196:199], v[158:161], v[118:121]
	v_mfma_f32_16x16x32_bf16 v[90:93], v[204:207], v[158:161], v[90:93]
	v_mfma_f32_16x16x32_bf16 v[58:61], v[212:215], v[158:161], v[58:61]
	v_mfma_f32_16x16x32_bf16 v[26:29], v[220:223], v[158:161], v[26:29]
	s_add_u32 m0, m0, 0x400
	v_add_u32_e32 v226, 0x14000, v224
	global_load_lds_dwordx4 v226, s[18:19]
	ds_read_b128 v[154:157], v229 offset:8192
	ds_read_b128 v[158:161], v230 offset:8192
	s_waitcnt lgkmcnt(2)
	v_mfma_f32_16x16x32_bf16 v[110:113], v[192:195], v[162:165], v[110:113]
	v_mfma_f32_16x16x32_bf16 v[78:81], v[200:203], v[162:165], v[78:81]
	v_mfma_f32_16x16x32_bf16 v[46:49], v[208:211], v[162:165], v[46:49]
	v_mfma_f32_16x16x32_bf16 v[18:21], v[216:219], v[162:165], v[18:21]
	s_add_u32 m0, m0, 0x400
	v_add_u32_e32 v226, 0x18000, v224
	global_load_lds_dwordx4 v226, s[18:19]
	v_mfma_f32_16x16x32_bf16 v[110:113], v[196:199], v[166:169], v[110:113]
	v_mfma_f32_16x16x32_bf16 v[78:81], v[204:207], v[166:169], v[78:81]
	v_mfma_f32_16x16x32_bf16 v[46:49], v[212:215], v[166:169], v[46:49]
	v_mfma_f32_16x16x32_bf16 v[18:21], v[220:223], v[166:169], v[18:21]
	s_add_u32 m0, m0, 0x400
	v_add_u32_e32 v226, 0x1c000, v224
	global_load_lds_dwordx4 v226, s[18:19]
	ds_read_b128 v[162:165], v229 offset:10240
	ds_read_b128 v[166:169], v230 offset:10240
	s_waitcnt lgkmcnt(2)
	v_mfma_f32_16x16x32_bf16 v[106:109], v[192:195], v[154:157], v[106:109]
	v_mfma_f32_16x16x32_bf16 v[74:77], v[200:203], v[154:157], v[74:77]
	v_mfma_f32_16x16x32_bf16 v[42:45], v[208:211], v[154:157], v[42:45]
	v_mfma_f32_16x16x32_bf16 v[14:17], v[216:219], v[154:157], v[14:17]
	s_add_u32 m0, s25, 17
	s_and_b32 m0, m0, 1
	s_lshl_b32 m0, m0, 14
	s_add_u32 m0, m0, 0x8000
	v_readfirstlane_b32 s32, v145
	s_lshl_b32 s32, s32, 2
	s_add_u32 m0, m0, s32
	v_mov_b32_e32 v226, v225
	global_load_lds_dwordx4 v226, s[18:19]
	v_mfma_f32_16x16x32_bf16 v[106:109], v[196:199], v[158:161], v[106:109]
	v_mfma_f32_16x16x32_bf16 v[74:77], v[204:207], v[158:161], v[74:77]
	v_mfma_f32_16x16x32_bf16 v[42:45], v[212:215], v[158:161], v[42:45]
	v_mfma_f32_16x16x32_bf16 v[14:17], v[220:223], v[158:161], v[14:17]
	s_add_u32 m0, m0, 0x400
	v_add_u32_e32 v226, 0x4000, v225
	global_load_lds_dwordx4 v226, s[18:19]
	ds_read_b128 v[154:157], v229 offset:12288
	ds_read_b128 v[158:161], v230 offset:12288
	s_waitcnt lgkmcnt(2)
	v_mfma_f32_16x16x32_bf16 v[98:101], v[192:195], v[162:165], v[98:101]
	v_mfma_f32_16x16x32_bf16 v[66:69], v[200:203], v[162:165], v[66:69]
	v_mfma_f32_16x16x32_bf16 v[34:37], v[208:211], v[162:165], v[34:37]
	v_mfma_f32_16x16x32_bf16 v[10:13], v[216:219], v[162:165], v[10:13]
	s_add_u32 m0, m0, 0x400
	v_add_u32_e32 v226, 0x8000, v225
	global_load_lds_dwordx4 v226, s[18:19]
	v_mfma_f32_16x16x32_bf16 v[98:101], v[196:199], v[166:169], v[98:101]
	v_mfma_f32_16x16x32_bf16 v[66:69], v[204:207], v[166:169], v[66:69]
	v_mfma_f32_16x16x32_bf16 v[34:37], v[212:215], v[166:169], v[34:37]
	v_mfma_f32_16x16x32_bf16 v[10:13], v[220:223], v[166:169], v[10:13]
	s_add_u32 m0, m0, 0x400
	v_add_u32_e32 v226, 0xc000, v225
	global_load_lds_dwordx4 v226, s[18:19]
	ds_read_b128 v[162:165], v229 offset:14336
	ds_read_b128 v[166:169], v230 offset:14336
	s_waitcnt lgkmcnt(2)
	v_mfma_f32_16x16x32_bf16 v[94:97], v[192:195], v[154:157], v[94:97]
	v_mfma_f32_16x16x32_bf16 v[62:65], v[200:203], v[154:157], v[62:65]
	v_mfma_f32_16x16x32_bf16 v[30:33], v[208:211], v[154:157], v[30:33]
	v_mfma_f32_16x16x32_bf16 v[6:9], v[216:219], v[154:157], v[6:9]
	v_mfma_f32_16x16x32_bf16 v[94:97], v[196:199], v[158:161], v[94:97]
	v_mfma_f32_16x16x32_bf16 v[62:65], v[204:207], v[158:161], v[62:65]
	v_mfma_f32_16x16x32_bf16 v[30:33], v[212:215], v[158:161], v[30:33]
	v_mfma_f32_16x16x32_bf16 v[6:9], v[220:223], v[158:161], v[6:9]
	s_waitcnt lgkmcnt(0)
	v_mfma_f32_16x16x32_bf16 v[82:85], v[192:195], v[162:165], v[82:85]
	v_mfma_f32_16x16x32_bf16 v[50:53], v[200:203], v[162:165], v[50:53]
	v_mfma_f32_16x16x32_bf16 v[22:25], v[208:211], v[162:165], v[22:25]
	v_mfma_f32_16x16x32_bf16 v[2:5], v[216:219], v[162:165], v[2:5]
	v_mfma_f32_16x16x32_bf16 v[82:85], v[196:199], v[166:169], v[82:85]
	v_mfma_f32_16x16x32_bf16 v[50:53], v[204:207], v[166:169], v[50:53]
	v_mfma_f32_16x16x32_bf16 v[22:25], v[212:215], v[166:169], v[22:25]
	v_mfma_f32_16x16x32_bf16 v[2:5], v[220:223], v[166:169], v[2:5]
	v_xor_b32_e32 v229, 0x4000, v229
	v_xor_b32_e32 v230, 0x4000, v230
	s_add_i32 s25, s25, 1
	s_cmp_lg_u32 s25, 15
	s_cbranch_scc1 .Lbk64_530
	s_waitcnt vmcnt(4)
	ds_read_b128 v[192:195], v227
	ds_read_b128 v[196:199], v228
	ds_read_b128 v[200:203], v227 offset:2048
	ds_read_b128 v[204:207], v228 offset:2048
	ds_read_b128 v[208:211], v227 offset:4096
	ds_read_b128 v[212:215], v228 offset:4096
	ds_read_b128 v[216:219], v227 offset:6144
	ds_read_b128 v[220:223], v228 offset:6144
	s_waitcnt vmcnt(0)
	s_barrier
	s_waitcnt lgkmcnt(0)
	ds_read_b128 v[154:157], v229 offset:0
	ds_read_b128 v[158:161], v230 offset:0
	ds_read_b128 v[162:165], v229 offset:2048
	ds_read_b128 v[166:169], v230 offset:2048
	s_waitcnt lgkmcnt(2)
	v_mfma_f32_16x16x32_bf16 v[126:129], v[192:195], v[154:157], v[126:129]
	v_mfma_f32_16x16x32_bf16 v[114:117], v[200:203], v[154:157], v[114:117]
	v_mfma_f32_16x16x32_bf16 v[86:89], v[208:211], v[154:157], v[86:89]
	v_mfma_f32_16x16x32_bf16 v[54:57], v[216:219], v[154:157], v[54:57]
	v_mfma_f32_16x16x32_bf16 v[126:129], v[196:199], v[158:161], v[126:129]
	v_mfma_f32_16x16x32_bf16 v[114:117], v[204:207], v[158:161], v[114:117]
	v_mfma_f32_16x16x32_bf16 v[86:89], v[212:215], v[158:161], v[86:89]
	v_mfma_f32_16x16x32_bf16 v[54:57], v[220:223], v[158:161], v[54:57]
	ds_read_b128 v[154:157], v229 offset:4096
	ds_read_b128 v[158:161], v230 offset:4096
	s_waitcnt lgkmcnt(2)
	v_mfma_f32_16x16x32_bf16 v[122:125], v[192:195], v[162:165], v[122:125]
	v_mfma_f32_16x16x32_bf16 v[102:105], v[200:203], v[162:165], v[102:105]
	v_mfma_f32_16x16x32_bf16 v[70:73], v[208:211], v[162:165], v[70:73]
	v_mfma_f32_16x16x32_bf16 v[38:41], v[216:219], v[162:165], v[38:41]
	v_mfma_f32_16x16x32_bf16 v[122:125], v[196:199], v[166:169], v[122:125]
	v_mfma_f32_16x16x32_bf16 v[102:105], v[204:207], v[166:169], v[102:105]
	v_mfma_f32_16x16x32_bf16 v[70:73], v[212:215], v[166:169], v[70:73]
	v_mfma_f32_16x16x32_bf16 v[38:41], v[220:223], v[166:169], v[38:41]
	ds_read_b128 v[162:165], v229 offset:6144
	ds_read_b128 v[166:169], v230 offset:6144
	s_waitcnt lgkmcnt(2)
	v_mfma_f32_16x16x32_bf16 v[118:121], v[192:195], v[154:157], v[118:121]
	v_mfma_f32_16x16x32_bf16 v[90:93], v[200:203], v[154:157], v[90:93]
	v_mfma_f32_16x16x32_bf16 v[58:61], v[208:211], v[154:157], v[58:61]
	v_mfma_f32_16x16x32_bf16 v[26:29], v[216:219], v[154:157], v[26:29]
	v_mfma_f32_16x16x32_bf16 v[118:121], v[196:199], v[158:161], v[118:121]
	v_mfma_f32_16x16x32_bf16 v[90:93], v[204:207], v[158:161], v[90:93]
	v_mfma_f32_16x16x32_bf16 v[58:61], v[212:215], v[158:161], v[58:61]
	v_mfma_f32_16x16x32_bf16 v[26:29], v[220:223], v[158:161], v[26:29]
	ds_read_b128 v[154:157], v229 offset:8192
	ds_read_b128 v[158:161], v230 offset:8192
	s_waitcnt lgkmcnt(2)
	v_mfma_f32_16x16x32_bf16 v[110:113], v[192:195], v[162:165], v[110:113]
	v_mfma_f32_16x16x32_bf16 v[78:81], v[200:203], v[162:165], v[78:81]
	v_mfma_f32_16x16x32_bf16 v[46:49], v[208:211], v[162:165], v[46:49]
	v_mfma_f32_16x16x32_bf16 v[18:21], v[216:219], v[162:165], v[18:21]
	v_mfma_f32_16x16x32_bf16 v[110:113], v[196:199], v[166:169], v[110:113]
	v_mfma_f32_16x16x32_bf16 v[78:81], v[204:207], v[166:169], v[78:81]
	v_mfma_f32_16x16x32_bf16 v[46:49], v[212:215], v[166:169], v[46:49]
	v_mfma_f32_16x16x32_bf16 v[18:21], v[220:223], v[166:169], v[18:21]
	ds_read_b128 v[162:165], v229 offset:10240
	ds_read_b128 v[166:169], v230 offset:10240
	s_waitcnt lgkmcnt(2)
	v_mfma_f32_16x16x32_bf16 v[106:109], v[192:195], v[154:157], v[106:109]
	v_mfma_f32_16x16x32_bf16 v[74:77], v[200:203], v[154:157], v[74:77]
	v_mfma_f32_16x16x32_bf16 v[42:45], v[208:211], v[154:157], v[42:45]
	v_mfma_f32_16x16x32_bf16 v[14:17], v[216:219], v[154:157], v[14:17]
	v_mfma_f32_16x16x32_bf16 v[106:109], v[196:199], v[158:161], v[106:109]
	v_mfma_f32_16x16x32_bf16 v[74:77], v[204:207], v[158:161], v[74:77]
	v_mfma_f32_16x16x32_bf16 v[42:45], v[212:215], v[158:161], v[42:45]
	v_mfma_f32_16x16x32_bf16 v[14:17], v[220:223], v[158:161], v[14:17]
	ds_read_b128 v[154:157], v229 offset:12288
	ds_read_b128 v[158:161], v230 offset:12288
	s_waitcnt lgkmcnt(2)
	v_mfma_f32_16x16x32_bf16 v[98:101], v[192:195], v[162:165], v[98:101]
	v_mfma_f32_16x16x32_bf16 v[66:69], v[200:203], v[162:165], v[66:69]
	v_mfma_f32_16x16x32_bf16 v[34:37], v[208:211], v[162:165], v[34:37]
	v_mfma_f32_16x16x32_bf16 v[10:13], v[216:219], v[162:165], v[10:13]
	v_mfma_f32_16x16x32_bf16 v[98:101], v[196:199], v[166:169], v[98:101]
	v_mfma_f32_16x16x32_bf16 v[66:69], v[204:207], v[166:169], v[66:69]
	v_mfma_f32_16x16x32_bf16 v[34:37], v[212:215], v[166:169], v[34:37]
	v_mfma_f32_16x16x32_bf16 v[10:13], v[220:223], v[166:169], v[10:13]
	ds_read_b128 v[162:165], v229 offset:14336
	ds_read_b128 v[166:169], v230 offset:14336
	s_waitcnt lgkmcnt(2)
	v_mfma_f32_16x16x32_bf16 v[94:97], v[192:195], v[154:157], v[94:97]
	v_mfma_f32_16x16x32_bf16 v[62:65], v[200:203], v[154:157], v[62:65]
	v_mfma_f32_16x16x32_bf16 v[30:33], v[208:211], v[154:157], v[30:33]
	v_mfma_f32_16x16x32_bf16 v[6:9], v[216:219], v[154:157], v[6:9]
	v_mfma_f32_16x16x32_bf16 v[94:97], v[196:199], v[158:161], v[94:97]
	v_mfma_f32_16x16x32_bf16 v[62:65], v[204:207], v[158:161], v[62:65]
	v_mfma_f32_16x16x32_bf16 v[30:33], v[212:215], v[158:161], v[30:33]
	v_mfma_f32_16x16x32_bf16 v[6:9], v[220:223], v[158:161], v[6:9]
	s_waitcnt lgkmcnt(0)
	v_mfma_f32_16x16x32_bf16 v[82:85], v[192:195], v[162:165], v[82:85]
	v_mfma_f32_16x16x32_bf16 v[50:53], v[200:203], v[162:165], v[50:53]
	v_mfma_f32_16x16x32_bf16 v[22:25], v[208:211], v[162:165], v[22:25]
	v_mfma_f32_16x16x32_bf16 v[2:5], v[216:219], v[162:165], v[2:5]
	v_mfma_f32_16x16x32_bf16 v[82:85], v[196:199], v[166:169], v[82:85]
	v_mfma_f32_16x16x32_bf16 v[50:53], v[204:207], v[166:169], v[50:53]
	v_mfma_f32_16x16x32_bf16 v[22:25], v[212:215], v[166:169], v[22:25]
	v_mfma_f32_16x16x32_bf16 v[2:5], v[220:223], v[166:169], v[2:5]
	s_nop 7
	s_nop 7
	s_waitcnt vmcnt(6)
	v_add_u32_e32 v145, v149, v147
	s_waitcnt vmcnt(0)
	s_waitcnt lgkmcnt(0)
	s_lshl_b32 s18, s16, 7
	s_ashr_i32 s19, s18, 31
	s_lshl_b64 s[18:19], s[18:19], 1
	v_and_b32_e32 v1, 0xfffffc0, v1
	v_lshl_or_b32 v1, v143, 2, v1
	v_mul_lo_u32 v1, v1, s33
	v_lshl_or_b32 v1, v142, 2, v1
	s_lshl_b32 s16, s16, 1
	s_ashr_i32 s17, s16, 31
	s_lshl_b64 s[16:17], s[16:17], 2
	s_add_i32 s24, s24, 1
	v_mov_b64_e32 v[162:163], v[62:63]
	v_mov_b64_e32 v[164:165], v[64:65]
	v_mov_b64_e32 v[166:167], v[30:31]
	v_mov_b64_e32 v[168:169], v[32:33]
	v_mov_b64_e32 v[130:131], v[22:23]
	v_mov_b64_e32 v[132:133], v[24:25]
	s_waitcnt lgkmcnt(0)
	v_mov_b64_e32 v[232:233], v[38:39]
	v_mov_b64_e32 v[234:235], v[40:41]
	v_mov_b64_e32 v[38:39], v[34:35]
	v_mov_b64_e32 v[40:41], v[36:37]
	v_mov_b64_e32 v[34:35], v[2:3]
	v_mov_b64_e32 v[36:37], v[4:5]
	s_nop 2
	v_mov_b32_e32 v2, v170
	v_mov_b64_e32 v[216:217], v[114:115]
	v_mov_b64_e32 v[218:219], v[116:117]
	v_add_u32_e32 v2, s4, v2
	v_ashrrev_i32_e32 v3, 31, v2
	v_lshlrev_b64 v[2:3], 11, v[2:3]
	v_lshl_add_u64 v[2:3], s[8:9], 0, v[2:3]
	v_lshl_add_u64 v[2:3], v[2:3], 0, s[18:19]
	v_mov_b64_e32 v[220:221], v[54:55]
	v_mov_b64_e32 v[222:223], v[56:57]
	v_mov_b64_e32 v[224:225], v[122:123]
	v_mov_b64_e32 v[226:227], v[124:125]
	v_mov_b64_e32 v[228:229], v[102:103]
	v_mov_b64_e32 v[230:231], v[104:105]
	v_mov_b64_e32 v[236:237], v[118:119]
	v_mov_b64_e32 v[238:239], v[120:121]
	v_mov_b64_e32 v[240:241], v[58:59]
	v_mov_b64_e32 v[242:243], v[60:61]
	v_mov_b64_e32 v[244:245], v[26:27]
	v_mov_b64_e32 v[246:247], v[28:29]
	v_mov_b64_e32 v[248:249], v[110:111]
	v_mov_b64_e32 v[250:251], v[112:113]
	v_mov_b64_e32 v[180:181], v[78:79]
	v_mov_b64_e32 v[182:183], v[80:81]
	v_mov_b64_e32 v[154:155], v[46:47]
	v_mov_b64_e32 v[156:157], v[48:49]
	v_mov_b64_e32 v[62:63], v[106:107]
	v_mov_b64_e32 v[64:65], v[108:109]
	v_mov_b64_e32 v[46:47], v[74:75]
	v_mov_b64_e32 v[48:49], v[76:77]
	v_mov_b64_e32 v[74:75], v[98:99]
	v_mov_b64_e32 v[76:77], v[100:101]
	v_mov_b64_e32 v[54:55], v[66:67]
	v_mov_b64_e32 v[56:57], v[68:69]
	v_mov_b64_e32 v[58:59], v[162:163]
	v_mov_b64_e32 v[60:61], v[164:165]
	v_mov_b64_e32 v[66:67], v[50:51]
	v_mov_b64_e32 v[68:69], v[52:53]
	flat_load_dwordx4 v[138:141], v[2:3]
	flat_load_dwordx4 v[122:125], v[2:3] offset:16
	flat_load_dwordx4 v[118:121], v[2:3] offset:32
	flat_load_dwordx4 v[114:117], v[2:3] offset:48
	flat_load_dwordx4 v[110:113], v[2:3] offset:64
	flat_load_dwordx4 v[106:109], v[2:3] offset:80
	flat_load_dwordx4 v[102:105], v[2:3] offset:96
	flat_load_dwordx4 v[98:101], v[2:3] offset:112
	s_waitcnt vmcnt(0) lgkmcnt(0)
	s_barrier
	s_nop 7
	ds_write2_b32 v1, v126, v224 offset1:16
	ds_write2_b32 v1, v127, v225 offset0:68 offset1:84
	ds_write2_b32 v1, v128, v226 offset0:136 offset1:152
	ds_write2_b32 v1, v129, v227 offset0:204 offset1:220
	ds_write2_b32 v1, v236, v248 offset0:32 offset1:48
	ds_write2_b32 v1, v237, v249 offset0:100 offset1:116
	ds_write2_b32 v1, v238, v250 offset0:168 offset1:184
	ds_write2_b32 v1, v239, v251 offset0:236 offset1:252
	v_mov_b64_e32 v[196:197], v[18:19]
	v_mov_b64_e32 v[198:199], v[20:21]
	v_mov_b64_e32 v[78:79], v[94:95]
	v_mov_b64_e32 v[80:81], v[96:97]
	v_add_u32_e32 v135, 0x3000, v1
	v_add_u32_e32 v134, 0x3400, v1
	v_mov_b32_e32 v136, v170
	v_mov_b64_e32 v[50:51], v[130:131]
	v_mov_b64_e32 v[52:53], v[132:133]
	v_lshlrev_b32_e32 v137, 16, v138
	s_nop 1
	v_add_u32_e32 v130, 0x1000, v1
	v_add_u32_e32 v131, 0x1400, v1
	v_add_u32_e32 v132, 0x2000, v1
	v_add_u32_e32 v133, 0x2400, v1
	ds_write2_b32 v130, v216, v228 offset0:64 offset1:80
	ds_write2_b32 v130, v217, v229 offset0:132 offset1:148
	ds_write2_b32 v130, v218, v230 offset0:200 offset1:216
	ds_write2_b32 v131, v219, v231 offset0:12 offset1:28
	ds_write2_b32 v130, v90, v180 offset0:96 offset1:112
	ds_write2_b32 v130, v91, v181 offset0:164 offset1:180
	ds_write2_b32 v130, v92, v182 offset0:232 offset1:248
	ds_write2_b32 v131, v93, v183 offset0:44 offset1:60
	ds_write2_b32 v132, v86, v70 offset0:128 offset1:144
	ds_write2_b32 v132, v87, v71 offset0:196 offset1:212
	ds_write2_b32 v133, v88, v72 offset0:8 offset1:24
	ds_write2_b32 v133, v89, v73 offset0:76 offset1:92
	ds_write2_b32 v132, v240, v154 offset0:160 offset1:176
	ds_write2_b32 v132, v241, v155 offset0:228 offset1:244
	ds_write2_b32 v133, v242, v156 offset0:40 offset1:56
	ds_write2_b32 v133, v243, v157 offset0:108 offset1:124
	ds_write2_b32 v135, v220, v232 offset0:192 offset1:208
	ds_write2_b32 v134, v221, v233 offset0:4 offset1:20
	ds_write2_b32 v134, v222, v234 offset0:72 offset1:88
	ds_write2_b32 v134, v223, v235 offset0:140 offset1:156
	ds_write2_b32 v135, v244, v196 offset0:224 offset1:240
	ds_write2_b32 v134, v245, v197 offset0:36 offset1:52
	ds_write2_b32 v134, v246, v198 offset0:104 offset1:120
	ds_write2_b32 v134, v247, v199 offset0:172 offset1:188
	s_waitcnt lgkmcnt(0)
	s_barrier
	v_mov_b64_e32 v[18:19], v[14:15]
	v_mov_b64_e32 v[20:21], v[16:17]
	v_add_u32_e32 v126, s4, v136
	v_ashrrev_i32_e32 v127, 31, v126
	v_lshlrev_b64 v[2:3], 11, v[126:127]
	v_lshl_add_u64 v[2:3], s[8:9], 0, v[2:3]
	v_lshl_add_u64 v[128:129], v[2:3], 0, s[18:19]
	v_mul_lo_u32 v136, v136, s33
	v_mov_b64_e32 v[22:23], v[10:11]
	v_mov_b64_e32 v[24:25], v[12:13]
	v_and_b32_e32 v138, 0xffff0000, v138
	v_mov_b64_e32 v[26:27], v[6:7]
	v_mov_b64_e32 v[28:29], v[8:9]
	flat_load_dwordx4 v[94:97], v[128:129] offset:128
	flat_load_dwordx4 v[90:93], v[128:129] offset:144
	flat_load_dwordx4 v[86:89], v[128:129] offset:160
	flat_load_dwordx4 v[70:73], v[128:129] offset:176
	flat_load_dwordx4 v[14:17], v[128:129] offset:192
	flat_load_dwordx4 v[10:13], v[128:129] offset:208
	flat_load_dwordx4 v[6:9], v[128:129] offset:224
	flat_load_dwordx4 v[2:5], v[128:129] offset:240
	ds_read_b128 v[142:145], v136
	ds_read_b128 v[154:157], v136 offset:16
	s_waitcnt lgkmcnt(0)
	v_add_f32_e32 v137, v142, v137
	v_add_f32_e32 v138, v143, v138
	v_cvt_pk_bf16_f32 v138, v137, v138
	v_lshlrev_b32_e32 v137, 16, v139
	v_and_b32_e32 v139, 0xffff0000, v139
	v_add_f32_e32 v137, v144, v137
	v_add_f32_e32 v139, v145, v139
	v_cvt_pk_bf16_f32 v139, v137, v139
	v_lshlrev_b32_e32 v137, 16, v140
	v_and_b32_e32 v140, 0xffff0000, v140
	v_add_f32_e32 v137, v154, v137
	v_add_f32_e32 v140, v155, v140
	v_cvt_pk_bf16_f32 v140, v137, v140
	v_lshlrev_b32_e32 v137, 16, v141
	v_and_b32_e32 v141, 0xffff0000, v141
	v_add_f32_e32 v137, v156, v137
	v_add_f32_e32 v141, v157, v141
	v_and_b32_e32 v142, 0xffff0000, v138
	v_cvt_pk_bf16_f32 v141, v137, v141
	v_lshlrev_b32_e32 v137, 16, v138
	v_mul_f32_e32 v153, v142, v142
	v_lshlrev_b32_e32 v143, 16, v139
	v_fmac_f32_e32 v153, v137, v137
	v_and_b32_e32 v144, 0xffff0000, v139
	v_fmac_f32_e32 v153, v143, v143
	v_lshlrev_b32_e32 v145, 16, v140
	v_fmac_f32_e32 v153, v144, v144
	ds_write_b128 v136, v[138:141]
	v_and_b32_e32 v147, 0xffff0000, v140
	v_lshlrev_b32_e32 v149, 16, v141
	v_and_b32_e32 v151, 0xffff0000, v141
	v_fmac_f32_e32 v153, v145, v145
	ds_read_b128 v[138:141], v136 offset:32
	ds_read_b128 v[142:145], v136 offset:48
	v_lshlrev_b32_e32 v137, 16, v122
	v_and_b32_e32 v122, 0xffff0000, v122
	v_fmac_f32_e32 v153, v147, v147
	s_waitcnt lgkmcnt(0)
	v_add_f32_e32 v137, v138, v137
	v_add_f32_e32 v122, v139, v122
	v_cvt_pk_bf16_f32 v122, v137, v122
	v_lshlrev_b32_e32 v137, 16, v123
	v_and_b32_e32 v123, 0xffff0000, v123
	v_add_f32_e32 v137, v140, v137
	v_add_f32_e32 v123, v141, v123
	v_cvt_pk_bf16_f32 v123, v137, v123
	v_lshlrev_b32_e32 v137, 16, v124
	v_and_b32_e32 v124, 0xffff0000, v124
	v_add_f32_e32 v137, v142, v137
	v_add_f32_e32 v124, v143, v124
	v_cvt_pk_bf16_f32 v124, v137, v124
	v_lshlrev_b32_e32 v137, 16, v125
	v_and_b32_e32 v125, 0xffff0000, v125
	v_add_f32_e32 v137, v144, v137
	v_add_f32_e32 v125, v145, v125
	v_and_b32_e32 v138, 0xffff0000, v122
	v_cvt_pk_bf16_f32 v125, v137, v125
	v_lshlrev_b32_e32 v137, 16, v122
	v_mul_f32_e32 v138, v138, v138
	v_lshlrev_b32_e32 v139, 16, v123
	v_fmac_f32_e32 v138, v137, v137
	v_and_b32_e32 v140, 0xffff0000, v123
	v_fmac_f32_e32 v138, v139, v139
	v_lshlrev_b32_e32 v141, 16, v124
	v_fmac_f32_e32 v138, v140, v140
	v_and_b32_e32 v142, 0xffff0000, v124
	v_fmac_f32_e32 v138, v141, v141
	v_lshlrev_b32_e32 v143, 16, v125
	v_fmac_f32_e32 v138, v142, v142
	v_fmac_f32_e32 v153, v149, v149
	v_and_b32_e32 v144, 0xffff0000, v125
	v_fmac_f32_e32 v138, v143, v143
	v_fmac_f32_e32 v153, v151, v151
	v_fmac_f32_e32 v138, v144, v144
	ds_write_b128 v136, v[122:125] offset:16
	v_add_f32_e32 v137, v153, v138
	ds_read_b128 v[122:125], v136 offset:64
	ds_read_b128 v[138:141], v136 offset:80
	v_lshlrev_b32_e32 v142, 16, v118
	v_and_b32_e32 v118, 0xffff0000, v118
	v_mov_b64_e32 v[30:31], v[42:43]
	v_mov_b64_e32 v[32:33], v[44:45]
	s_waitcnt lgkmcnt(0)
	v_add_f32_e32 v122, v122, v142
	v_add_f32_e32 v118, v123, v118
	v_cvt_pk_bf16_f32 v118, v122, v118
	v_lshlrev_b32_e32 v122, 16, v119
	v_and_b32_e32 v119, 0xffff0000, v119
	v_add_f32_e32 v122, v124, v122
	v_add_f32_e32 v119, v125, v119
	v_cvt_pk_bf16_f32 v119, v122, v119
	v_lshlrev_b32_e32 v122, 16, v120
	v_and_b32_e32 v120, 0xffff0000, v120
	v_add_f32_e32 v122, v138, v122
	v_add_f32_e32 v120, v139, v120
	v_cvt_pk_bf16_f32 v120, v122, v120
	v_lshlrev_b32_e32 v122, 16, v121
	v_and_b32_e32 v121, 0xffff0000, v121
	v_add_f32_e32 v122, v140, v122
	v_add_f32_e32 v121, v141, v121
	v_and_b32_e32 v123, 0xffff0000, v118
	v_cvt_pk_bf16_f32 v121, v122, v121
	v_lshlrev_b32_e32 v122, 16, v118
	v_mul_f32_e32 v123, v123, v123
	v_lshlrev_b32_e32 v124, 16, v119
	v_fmac_f32_e32 v123, v122, v122
	v_and_b32_e32 v125, 0xffff0000, v119
	v_fmac_f32_e32 v123, v124, v124
	v_lshlrev_b32_e32 v138, 16, v120
	v_fmac_f32_e32 v123, v125, v125
	v_and_b32_e32 v139, 0xffff0000, v120
	v_fmac_f32_e32 v123, v138, v138
	v_lshlrev_b32_e32 v140, 16, v121
	v_fmac_f32_e32 v123, v139, v139
	v_and_b32_e32 v141, 0xffff0000, v121
	v_fmac_f32_e32 v123, v140, v140
	v_fmac_f32_e32 v123, v141, v141
	ds_write_b128 v136, v[118:121] offset:32
	v_add_f32_e32 v137, v137, v123
	ds_read_b128 v[118:121], v136 offset:96
	ds_read_b128 v[122:125], v136 offset:112
	v_lshlrev_b32_e32 v138, 16, v114
	v_and_b32_e32 v114, 0xffff0000, v114
	v_mov_b64_e32 v[42:43], v[166:167]
	v_mov_b64_e32 v[44:45], v[168:169]
	s_waitcnt lgkmcnt(0)
	v_add_f32_e32 v118, v118, v138
	v_add_f32_e32 v114, v119, v114
	v_cvt_pk_bf16_f32 v114, v118, v114
	v_lshlrev_b32_e32 v118, 16, v115
	v_and_b32_e32 v115, 0xffff0000, v115
	v_add_f32_e32 v118, v120, v118
	v_add_f32_e32 v115, v121, v115
	v_cvt_pk_bf16_f32 v115, v118, v115
	v_lshlrev_b32_e32 v118, 16, v116
	v_and_b32_e32 v116, 0xffff0000, v116
	v_add_f32_e32 v118, v122, v118
	v_add_f32_e32 v116, v123, v116
	v_cvt_pk_bf16_f32 v116, v118, v116
	v_lshlrev_b32_e32 v118, 16, v117
	v_and_b32_e32 v117, 0xffff0000, v117
	v_add_f32_e32 v118, v124, v118
	v_add_f32_e32 v117, v125, v117
	v_and_b32_e32 v119, 0xffff0000, v114
	v_cvt_pk_bf16_f32 v117, v118, v117
	v_lshlrev_b32_e32 v118, 16, v114
	v_mul_f32_e32 v119, v119, v119
	v_lshlrev_b32_e32 v120, 16, v115
	v_fmac_f32_e32 v119, v118, v118
	v_and_b32_e32 v121, 0xffff0000, v115
	v_fmac_f32_e32 v119, v120, v120
	v_lshlrev_b32_e32 v122, 16, v116
	v_fmac_f32_e32 v119, v121, v121
	v_and_b32_e32 v123, 0xffff0000, v116
	v_fmac_f32_e32 v119, v122, v122
	v_lshlrev_b32_e32 v124, 16, v117
	v_fmac_f32_e32 v119, v123, v123
	v_and_b32_e32 v125, 0xffff0000, v117
	v_fmac_f32_e32 v119, v124, v124
	v_fmac_f32_e32 v119, v125, v125
	ds_write_b128 v136, v[114:117] offset:48
	v_add_f32_e32 v122, v137, v119
	ds_read_b128 v[114:117], v136 offset:128
	ds_read_b128 v[118:121], v136 offset:144
	v_lshlrev_b32_e32 v123, 16, v110
	v_and_b32_e32 v110, 0xffff0000, v110
	s_waitcnt lgkmcnt(0)
	v_add_f32_e32 v114, v114, v123
	v_add_f32_e32 v110, v115, v110
	v_cvt_pk_bf16_f32 v110, v114, v110
	v_lshlrev_b32_e32 v114, 16, v111
	v_and_b32_e32 v111, 0xffff0000, v111
	v_add_f32_e32 v114, v116, v114
	v_add_f32_e32 v111, v117, v111
	v_cvt_pk_bf16_f32 v111, v114, v111
	v_lshlrev_b32_e32 v114, 16, v112
	v_and_b32_e32 v112, 0xffff0000, v112
	v_add_f32_e32 v114, v118, v114
	v_add_f32_e32 v112, v119, v112
	v_cvt_pk_bf16_f32 v112, v114, v112
	v_lshlrev_b32_e32 v114, 16, v113
	v_and_b32_e32 v113, 0xffff0000, v113
	v_add_f32_e32 v114, v120, v114
	v_add_f32_e32 v113, v121, v113
	v_and_b32_e32 v115, 0xffff0000, v110
	v_cvt_pk_bf16_f32 v113, v114, v113
	v_lshlrev_b32_e32 v114, 16, v110
	v_mul_f32_e32 v115, v115, v115
	v_lshlrev_b32_e32 v116, 16, v111
	v_fmac_f32_e32 v115, v114, v114
	v_and_b32_e32 v117, 0xffff0000, v111
	v_fmac_f32_e32 v115, v116, v116
	v_lshlrev_b32_e32 v118, 16, v112
	v_fmac_f32_e32 v115, v117, v117
	v_and_b32_e32 v119, 0xffff0000, v112
	v_fmac_f32_e32 v115, v118, v118
	v_lshlrev_b32_e32 v120, 16, v113
	v_fmac_f32_e32 v115, v119, v119
	v_and_b32_e32 v121, 0xffff0000, v113
	v_fmac_f32_e32 v115, v120, v120
	v_fmac_f32_e32 v115, v121, v121
	ds_write_b128 v136, v[110:113] offset:64
	v_add_f32_e32 v118, v122, v115
	ds_read_b128 v[110:113], v136 offset:160
	ds_read_b128 v[114:117], v136 offset:176
	v_lshlrev_b32_e32 v119, 16, v106
	v_and_b32_e32 v106, 0xffff0000, v106
	s_waitcnt lgkmcnt(0)
	v_add_f32_e32 v110, v110, v119
	v_add_f32_e32 v106, v111, v106
	v_cvt_pk_bf16_f32 v106, v110, v106
	v_lshlrev_b32_e32 v110, 16, v107
	v_and_b32_e32 v107, 0xffff0000, v107
	v_add_f32_e32 v110, v112, v110
	v_add_f32_e32 v107, v113, v107
	v_cvt_pk_bf16_f32 v107, v110, v107
	v_lshlrev_b32_e32 v110, 16, v108
	v_and_b32_e32 v108, 0xffff0000, v108
	v_add_f32_e32 v110, v114, v110
	v_add_f32_e32 v108, v115, v108
	v_cvt_pk_bf16_f32 v108, v110, v108
	v_lshlrev_b32_e32 v110, 16, v109
	v_and_b32_e32 v109, 0xffff0000, v109
	v_add_f32_e32 v110, v116, v110
	v_add_f32_e32 v109, v117, v109
	v_and_b32_e32 v111, 0xffff0000, v106
	v_cvt_pk_bf16_f32 v109, v110, v109
	v_lshlrev_b32_e32 v110, 16, v106
	v_mul_f32_e32 v111, v111, v111
	v_lshlrev_b32_e32 v112, 16, v107
	v_fmac_f32_e32 v111, v110, v110
	v_and_b32_e32 v113, 0xffff0000, v107
	v_fmac_f32_e32 v111, v112, v112
	v_lshlrev_b32_e32 v114, 16, v108
	v_fmac_f32_e32 v111, v113, v113
	v_and_b32_e32 v115, 0xffff0000, v108
	v_fmac_f32_e32 v111, v114, v114
	v_lshlrev_b32_e32 v116, 16, v109
	v_fmac_f32_e32 v111, v115, v115
	v_and_b32_e32 v117, 0xffff0000, v109
	v_fmac_f32_e32 v111, v116, v116
	v_fmac_f32_e32 v111, v117, v117
	ds_write_b128 v136, v[106:109] offset:80
	v_add_f32_e32 v114, v118, v111
	ds_read_b128 v[106:109], v136 offset:192
	ds_read_b128 v[110:113], v136 offset:208
	v_lshlrev_b32_e32 v115, 16, v102
	v_and_b32_e32 v102, 0xffff0000, v102
	s_waitcnt lgkmcnt(0)
	v_add_f32_e32 v106, v106, v115
	v_add_f32_e32 v102, v107, v102
	v_cvt_pk_bf16_f32 v102, v106, v102
	v_lshlrev_b32_e32 v106, 16, v103
	v_and_b32_e32 v103, 0xffff0000, v103
	v_add_f32_e32 v106, v108, v106
	v_add_f32_e32 v103, v109, v103
	v_cvt_pk_bf16_f32 v103, v106, v103
	v_lshlrev_b32_e32 v106, 16, v104
	v_and_b32_e32 v104, 0xffff0000, v104
	v_add_f32_e32 v106, v110, v106
	v_add_f32_e32 v104, v111, v104
	v_cvt_pk_bf16_f32 v104, v106, v104
	v_lshlrev_b32_e32 v106, 16, v105
	v_and_b32_e32 v105, 0xffff0000, v105
	v_add_f32_e32 v106, v112, v106
	v_add_f32_e32 v105, v113, v105
	v_and_b32_e32 v107, 0xffff0000, v102
	v_cvt_pk_bf16_f32 v105, v106, v105
	v_lshlrev_b32_e32 v106, 16, v102
	v_mul_f32_e32 v107, v107, v107
	v_lshlrev_b32_e32 v108, 16, v103
	v_fmac_f32_e32 v107, v106, v106
	v_and_b32_e32 v109, 0xffff0000, v103
	v_fmac_f32_e32 v107, v108, v108
	v_lshlrev_b32_e32 v110, 16, v104
	v_fmac_f32_e32 v107, v109, v109
	v_and_b32_e32 v111, 0xffff0000, v104
	v_fmac_f32_e32 v107, v110, v110
	v_lshlrev_b32_e32 v112, 16, v105
	v_fmac_f32_e32 v107, v111, v111
	v_and_b32_e32 v113, 0xffff0000, v105
	v_fmac_f32_e32 v107, v112, v112
	v_fmac_f32_e32 v107, v113, v113
	ds_write_b128 v136, v[102:105] offset:96
	v_add_f32_e32 v110, v114, v107
	ds_read_b128 v[102:105], v136 offset:224
	ds_read_b128 v[106:109], v136 offset:240
	v_lshlrev_b32_e32 v111, 16, v98
	v_and_b32_e32 v98, 0xffff0000, v98
	s_waitcnt lgkmcnt(0)
	v_add_f32_e32 v102, v102, v111
	v_add_f32_e32 v98, v103, v98
	v_cvt_pk_bf16_f32 v98, v102, v98
	v_lshlrev_b32_e32 v102, 16, v99
	v_and_b32_e32 v99, 0xffff0000, v99
	v_add_f32_e32 v102, v104, v102
	v_add_f32_e32 v99, v105, v99
	v_cvt_pk_bf16_f32 v99, v102, v99
	v_lshlrev_b32_e32 v102, 16, v100
	v_and_b32_e32 v100, 0xffff0000, v100
	v_add_f32_e32 v102, v106, v102
	v_add_f32_e32 v100, v107, v100
	v_cvt_pk_bf16_f32 v100, v102, v100
	v_lshlrev_b32_e32 v102, 16, v101
	v_and_b32_e32 v101, 0xffff0000, v101
	v_add_f32_e32 v102, v108, v102
	v_add_f32_e32 v101, v109, v101
	v_and_b32_e32 v103, 0xffff0000, v98
	v_cvt_pk_bf16_f32 v101, v102, v101
	v_lshlrev_b32_e32 v102, 16, v98
	v_mul_f32_e32 v103, v103, v103
	v_lshlrev_b32_e32 v104, 16, v99
	v_fmac_f32_e32 v103, v102, v102
	v_and_b32_e32 v105, 0xffff0000, v99
	v_fmac_f32_e32 v103, v104, v104
	v_lshlrev_b32_e32 v106, 16, v100
	v_fmac_f32_e32 v103, v105, v105
	v_and_b32_e32 v107, 0xffff0000, v100
	v_fmac_f32_e32 v103, v106, v106
	v_lshlrev_b32_e32 v108, 16, v101
	v_fmac_f32_e32 v103, v107, v107
	v_and_b32_e32 v109, 0xffff0000, v101
	v_fmac_f32_e32 v103, v108, v108
	ds_write_b128 v136, v[98:101] offset:112
	v_and_b32_e32 v102, 63, v170
	v_lshrrev_b32_e32 v108, 3, v102
	v_sub_u32_e32 v108, v108, v102
	v_and_b32_e32 v102, 7, v102
	v_lshlrev_b32_e32 v102, 4, v102
	v_mul_i32_i24_e32 v98, 0x800, v108
	v_add_u32_e32 v98, v98, v102
	v_mul_i32_i24_e32 v108, 0x110, v108
	v_add3_u32 v108, v108, v102, v136
	s_waitcnt lgkmcnt(0)
	ds_read_b128 v[104:107], v108 offset:0
	v_mov_b32_e32 v100, v98
	v_ashrrev_i32_e32 v101, 31, v100
	v_lshl_add_u64 v[116:117], v[100:101], 0, v[128:129]
	s_waitcnt lgkmcnt(0)
	global_store_dwordx4 v[116:117], v[104:107], off
	ds_read_b128 v[112:115], v108 offset:2176
	v_add_u32_e32 v100, 0x4000, v98
	v_ashrrev_i32_e32 v101, 31, v100
	v_lshl_add_u64 v[116:117], v[100:101], 0, v[128:129]
	s_waitcnt lgkmcnt(0)
	global_store_dwordx4 v[116:117], v[112:115], off
	ds_read_b128 v[104:107], v108 offset:4352
	v_add_u32_e32 v100, 0x8000, v98
	v_ashrrev_i32_e32 v101, 31, v100
	v_lshl_add_u64 v[116:117], v[100:101], 0, v[128:129]
	s_waitcnt lgkmcnt(0)
	global_store_dwordx4 v[116:117], v[104:107], off
	ds_read_b128 v[112:115], v108 offset:6528
	v_add_u32_e32 v100, 0xc000, v98
	v_ashrrev_i32_e32 v101, 31, v100
	v_lshl_add_u64 v[116:117], v[100:101], 0, v[128:129]
	s_waitcnt lgkmcnt(0)
	global_store_dwordx4 v[116:117], v[112:115], off
	ds_read_b128 v[104:107], v108 offset:8704
	v_add_u32_e32 v100, 0x10000, v98
	v_ashrrev_i32_e32 v101, 31, v100
	v_lshl_add_u64 v[116:117], v[100:101], 0, v[128:129]
	s_waitcnt lgkmcnt(0)
	global_store_dwordx4 v[116:117], v[104:107], off
	ds_read_b128 v[112:115], v108 offset:10880
	v_add_u32_e32 v100, 0x14000, v98
	v_ashrrev_i32_e32 v101, 31, v100
	v_lshl_add_u64 v[116:117], v[100:101], 0, v[128:129]
	s_waitcnt lgkmcnt(0)
	global_store_dwordx4 v[116:117], v[112:115], off
	ds_read_b128 v[104:107], v108 offset:13056
	v_add_u32_e32 v100, 0x18000, v98
	v_ashrrev_i32_e32 v101, 31, v100
	v_lshl_add_u64 v[116:117], v[100:101], 0, v[128:129]
	s_waitcnt lgkmcnt(0)
	global_store_dwordx4 v[116:117], v[104:107], off
	ds_read_b128 v[112:115], v108 offset:15232
	v_add_u32_e32 v100, 0x1c000, v98
	v_ashrrev_i32_e32 v101, 31, v100
	v_lshl_add_u64 v[116:117], v[100:101], 0, v[128:129]
	s_waitcnt lgkmcnt(0)
	global_store_dwordx4 v[116:117], v[112:115], off
	v_fmac_f32_e32 v103, v109, v109
	v_add_f32_e32 v102, v110, v103
	v_lshlrev_b64 v[98:99], 6, v[126:127]
	v_lshl_add_u64 v[98:99], s[6:7], 0, v[98:99]
	v_lshl_add_u64 v[98:99], v[98:99], 0, s[16:17]
	flat_store_dword v[98:99], v102
	s_waitcnt lgkmcnt(0)
	s_barrier
	ds_write2_b32 v1, v62, v74 offset1:16
	ds_write2_b32 v1, v63, v75 offset0:68 offset1:84
	ds_write2_b32 v1, v64, v76 offset0:136 offset1:152
	ds_write2_b32 v1, v65, v77 offset0:204 offset1:220
	ds_write2_b32 v1, v78, v82 offset0:32 offset1:48
	ds_write2_b32 v1, v79, v83 offset0:100 offset1:116
	ds_write2_b32 v1, v80, v84 offset0:168 offset1:184
	ds_write2_b32 v1, v81, v85 offset0:236 offset1:252
	ds_write2_b32 v130, v46, v54 offset0:64 offset1:80
	ds_write2_b32 v130, v47, v55 offset0:132 offset1:148
	ds_write2_b32 v130, v48, v56 offset0:200 offset1:216
	ds_write2_b32 v131, v49, v57 offset0:12 offset1:28
	ds_write2_b32 v130, v58, v66 offset0:96 offset1:112
	ds_write2_b32 v130, v59, v67 offset0:164 offset1:180
	ds_write2_b32 v130, v60, v68 offset0:232 offset1:248
	ds_write2_b32 v131, v61, v69 offset0:44 offset1:60
	ds_write2_b32 v132, v30, v38 offset0:128 offset1:144
	ds_write2_b32 v132, v31, v39 offset0:196 offset1:212
	ds_write2_b32 v133, v32, v40 offset0:8 offset1:24
	ds_write2_b32 v133, v33, v41 offset0:76 offset1:92
	ds_write2_b32 v132, v42, v50 offset0:160 offset1:176
	ds_write2_b32 v132, v43, v51 offset0:228 offset1:244
	ds_write2_b32 v133, v44, v52 offset0:40 offset1:56
	ds_write2_b32 v133, v45, v53 offset0:108 offset1:124
	ds_write2_b32 v135, v18, v22 offset0:192 offset1:208
	ds_write2_b32 v134, v19, v23 offset0:4 offset1:20
	ds_write2_b32 v134, v20, v24 offset0:72 offset1:88
	ds_write2_b32 v134, v21, v25 offset0:140 offset1:156
	ds_write2_b32 v135, v26, v34 offset0:224 offset1:240
	ds_write2_b32 v134, v27, v35 offset0:36 offset1:52
	ds_write2_b32 v134, v28, v36 offset0:104 offset1:120
	ds_write2_b32 v134, v29, v37 offset0:172 offset1:188
	v_mov_b32_e32 v1, v170
	s_waitcnt lgkmcnt(0)
	s_barrier
	s_waitcnt vmcnt(0)
	v_lshlrev_b32_e32 v28, 16, v94
	v_add_u32_e32 v18, s4, v1
	v_ashrrev_i32_e32 v19, 31, v18
	v_lshlrev_b64 v[20:21], 11, v[18:19]
	v_lshl_add_u64 v[20:21], s[38:39], 0, v[20:21]
	v_mul_lo_u32 v1, v1, s33
	v_lshl_add_u64 v[32:33], v[20:21], 0, s[18:19]
	ds_read_b128 v[20:23], v1
	ds_read_b128 v[24:27], v1 offset:16
	s_mov_b64 s[4:5], 0
	s_waitcnt lgkmcnt(1)
	v_add_f32_e32 v20, v20, v28
	v_and_b32_e32 v28, 0xffff0000, v94
	v_add_f32_e32 v21, v21, v28
	v_cvt_pk_bf16_f32 v28, v20, v21
	v_and_b32_e32 v21, 0xffff0000, v95
	v_lshlrev_b32_e32 v20, 16, v95
	v_add_f32_e32 v21, v23, v21
	v_add_f32_e32 v20, v22, v20
	v_cvt_pk_bf16_f32 v29, v20, v21
	v_and_b32_e32 v21, 0xffff0000, v96
	v_lshlrev_b32_e32 v20, 16, v96
	s_waitcnt lgkmcnt(0)
	v_add_f32_e32 v21, v25, v21
	v_add_f32_e32 v20, v24, v20
	v_cvt_pk_bf16_f32 v30, v20, v21
	v_and_b32_e32 v21, 0xffff0000, v97
	v_lshlrev_b32_e32 v20, 16, v97
	v_add_f32_e32 v21, v27, v21
	v_add_f32_e32 v20, v26, v20
	v_cvt_pk_bf16_f32 v31, v20, v21
	v_and_b32_e32 v21, 0xffff0000, v28
	v_lshlrev_b32_e32 v20, 16, v28
	v_mul_f32_e32 v34, v21, v21
	v_lshlrev_b32_e32 v22, 16, v29
	v_fmac_f32_e32 v34, v20, v20
	v_and_b32_e32 v23, 0xffff0000, v29
	v_fmac_f32_e32 v34, v22, v22
	v_lshlrev_b32_e32 v24, 16, v30
	v_fmac_f32_e32 v34, v23, v23
	v_and_b32_e32 v25, 0xffff0000, v30
	v_fmac_f32_e32 v34, v24, v24
	v_add_co_u32_e32 v20, vcc, s90, v32
	v_lshlrev_b32_e32 v26, 16, v31
	v_fmac_f32_e32 v34, v25, v25
	v_addc_co_u32_e32 v21, vcc, 0, v33, vcc
	v_and_b32_e32 v27, 0xffff0000, v31
	v_fmac_f32_e32 v34, v26, v26
	v_mul_u32_u24_e32 v35, 0x110, v170
	ds_write_b128 v35, v[28:31]
	v_fmac_f32_e32 v34, v27, v27
	ds_read_b128 v[22:25], v1 offset:32
	ds_read_b128 v[26:29], v1 offset:48
	v_lshlrev_b32_e32 v30, 16, v90
	s_waitcnt lgkmcnt(0)
	v_add_f32_e32 v22, v22, v30
	v_and_b32_e32 v30, 0xffff0000, v90
	v_add_f32_e32 v23, v23, v30
	v_cvt_pk_bf16_f32 v22, v22, v23
	v_lshlrev_b32_e32 v23, 16, v91
	v_add_f32_e32 v23, v24, v23
	v_and_b32_e32 v24, 0xffff0000, v91
	v_add_f32_e32 v24, v25, v24
	v_cvt_pk_bf16_f32 v23, v23, v24
	v_lshlrev_b32_e32 v24, 16, v92
	v_and_b32_e32 v25, 0xffff0000, v92
	v_add_f32_e32 v24, v26, v24
	v_add_f32_e32 v25, v27, v25
	v_cvt_pk_bf16_f32 v24, v24, v25
	v_lshlrev_b32_e32 v25, 16, v93
	v_and_b32_e32 v26, 0xffff0000, v93
	v_add_f32_e32 v25, v28, v25
	v_add_f32_e32 v26, v29, v26
	v_and_b32_e32 v27, 0xffff0000, v22
	v_cvt_pk_bf16_f32 v25, v25, v26
	v_lshlrev_b32_e32 v26, 16, v22
	v_mul_f32_e32 v27, v27, v27
	v_lshlrev_b32_e32 v28, 16, v23
	v_fmac_f32_e32 v27, v26, v26
	v_and_b32_e32 v29, 0xffff0000, v23
	v_fmac_f32_e32 v27, v28, v28
	v_lshlrev_b32_e32 v30, 16, v24
	v_fmac_f32_e32 v27, v29, v29
	v_and_b32_e32 v31, 0xffff0000, v24
	v_fmac_f32_e32 v27, v30, v30
	v_lshlrev_b32_e32 v32, 16, v25
	v_fmac_f32_e32 v27, v31, v31
	v_and_b32_e32 v33, 0xffff0000, v25
	v_fmac_f32_e32 v27, v32, v32
	v_fmac_f32_e32 v27, v33, v33
	ds_write_b128 v35, v[22:25] offset:16
	v_add_f32_e32 v30, v34, v27
	ds_read_b128 v[22:25], v1 offset:64
	ds_read_b128 v[26:29], v1 offset:80
	v_lshlrev_b32_e32 v31, 16, v86
	s_waitcnt lgkmcnt(0)
	v_add_f32_e32 v22, v22, v31
	v_and_b32_e32 v31, 0xffff0000, v86
	v_add_f32_e32 v23, v23, v31
	v_cvt_pk_bf16_f32 v22, v22, v23
	v_lshlrev_b32_e32 v23, 16, v87
	v_add_f32_e32 v23, v24, v23
	v_and_b32_e32 v24, 0xffff0000, v87
	v_add_f32_e32 v24, v25, v24
	v_cvt_pk_bf16_f32 v23, v23, v24
	v_lshlrev_b32_e32 v24, 16, v88
	v_and_b32_e32 v25, 0xffff0000, v88
	v_add_f32_e32 v24, v26, v24
	v_add_f32_e32 v25, v27, v25
	v_cvt_pk_bf16_f32 v24, v24, v25
	v_lshlrev_b32_e32 v25, 16, v89
	v_and_b32_e32 v26, 0xffff0000, v89
	v_add_f32_e32 v25, v28, v25
	v_add_f32_e32 v26, v29, v26
	v_and_b32_e32 v27, 0xffff0000, v22
	v_cvt_pk_bf16_f32 v25, v25, v26
	v_lshlrev_b32_e32 v26, 16, v22
	v_mul_f32_e32 v27, v27, v27
	v_lshlrev_b32_e32 v28, 16, v23
	v_fmac_f32_e32 v27, v26, v26
	v_and_b32_e32 v29, 0xffff0000, v23
	v_fmac_f32_e32 v27, v28, v28
	v_lshlrev_b32_e32 v31, 16, v24
	v_fmac_f32_e32 v27, v29, v29
	v_and_b32_e32 v32, 0xffff0000, v24
	v_fmac_f32_e32 v27, v31, v31
	v_lshlrev_b32_e32 v33, 16, v25
	v_fmac_f32_e32 v27, v32, v32
	v_and_b32_e32 v34, 0xffff0000, v25
	v_fmac_f32_e32 v27, v33, v33
	v_fmac_f32_e32 v27, v34, v34
	ds_write_b128 v35, v[22:25] offset:32
	v_add_f32_e32 v30, v30, v27
	ds_read_b128 v[22:25], v1 offset:96
	ds_read_b128 v[26:29], v1 offset:112
	v_lshlrev_b32_e32 v31, 16, v70
	s_waitcnt lgkmcnt(0)
	v_add_f32_e32 v22, v22, v31
	v_and_b32_e32 v31, 0xffff0000, v70
	v_add_f32_e32 v23, v23, v31
	v_cvt_pk_bf16_f32 v22, v22, v23
	v_lshlrev_b32_e32 v23, 16, v71
	v_add_f32_e32 v23, v24, v23
	v_and_b32_e32 v24, 0xffff0000, v71
	v_add_f32_e32 v24, v25, v24
	v_cvt_pk_bf16_f32 v23, v23, v24
	v_lshlrev_b32_e32 v24, 16, v72
	v_and_b32_e32 v25, 0xffff0000, v72
	v_add_f32_e32 v24, v26, v24
	v_add_f32_e32 v25, v27, v25
	v_cvt_pk_bf16_f32 v24, v24, v25
	v_lshlrev_b32_e32 v25, 16, v73
	v_and_b32_e32 v26, 0xffff0000, v73
	v_add_f32_e32 v25, v28, v25
	v_add_f32_e32 v26, v29, v26
	v_and_b32_e32 v27, 0xffff0000, v22
	v_cvt_pk_bf16_f32 v25, v25, v26
	v_lshlrev_b32_e32 v26, 16, v22
	v_mul_f32_e32 v27, v27, v27
	v_lshlrev_b32_e32 v28, 16, v23
	v_fmac_f32_e32 v27, v26, v26
	v_and_b32_e32 v29, 0xffff0000, v23
	v_fmac_f32_e32 v27, v28, v28
	v_lshlrev_b32_e32 v31, 16, v24
	v_fmac_f32_e32 v27, v29, v29
	v_and_b32_e32 v32, 0xffff0000, v24
	v_fmac_f32_e32 v27, v31, v31
	v_lshlrev_b32_e32 v33, 16, v25
	v_fmac_f32_e32 v27, v32, v32
	v_and_b32_e32 v34, 0xffff0000, v25
	v_fmac_f32_e32 v27, v33, v33
	v_fmac_f32_e32 v27, v34, v34
	ds_write_b128 v35, v[22:25] offset:48
	v_add_f32_e32 v30, v30, v27
	ds_read_b128 v[22:25], v1 offset:128
	ds_read_b128 v[26:29], v1 offset:144
	v_lshlrev_b32_e32 v31, 16, v14
	v_and_b32_e32 v14, 0xffff0000, v14
	s_waitcnt lgkmcnt(0)
	v_add_f32_e32 v22, v22, v31
	v_add_f32_e32 v14, v23, v14
	v_cvt_pk_bf16_f32 v14, v22, v14
	v_lshlrev_b32_e32 v22, 16, v15
	v_and_b32_e32 v15, 0xffff0000, v15
	v_add_f32_e32 v22, v24, v22
	v_add_f32_e32 v15, v25, v15
	v_cvt_pk_bf16_f32 v15, v22, v15
	v_lshlrev_b32_e32 v22, 16, v16
	v_and_b32_e32 v16, 0xffff0000, v16
	v_add_f32_e32 v22, v26, v22
	v_add_f32_e32 v16, v27, v16
	v_cvt_pk_bf16_f32 v16, v22, v16
	v_lshlrev_b32_e32 v22, 16, v17
	v_and_b32_e32 v17, 0xffff0000, v17
	v_add_f32_e32 v22, v28, v22
	v_add_f32_e32 v17, v29, v17
	v_and_b32_e32 v23, 0xffff0000, v14
	v_cvt_pk_bf16_f32 v17, v22, v17
	v_lshlrev_b32_e32 v22, 16, v14
	v_mul_f32_e32 v23, v23, v23
	v_lshlrev_b32_e32 v24, 16, v15
	v_fmac_f32_e32 v23, v22, v22
	v_and_b32_e32 v25, 0xffff0000, v15
	v_fmac_f32_e32 v23, v24, v24
	v_lshlrev_b32_e32 v26, 16, v16
	v_fmac_f32_e32 v23, v25, v25
	v_and_b32_e32 v27, 0xffff0000, v16
	v_fmac_f32_e32 v23, v26, v26
	v_lshlrev_b32_e32 v28, 16, v17
	v_fmac_f32_e32 v23, v27, v27
	v_and_b32_e32 v29, 0xffff0000, v17
	v_fmac_f32_e32 v23, v28, v28
	v_fmac_f32_e32 v23, v29, v29
	ds_write_b128 v35, v[14:17] offset:64
	v_add_f32_e32 v26, v30, v23
	ds_read_b128 v[14:17], v1 offset:160
	ds_read_b128 v[22:25], v1 offset:176
	v_lshlrev_b32_e32 v27, 16, v10
	v_and_b32_e32 v10, 0xffff0000, v10
	s_waitcnt lgkmcnt(0)
	v_add_f32_e32 v14, v14, v27
	v_add_f32_e32 v10, v15, v10
	v_cvt_pk_bf16_f32 v10, v14, v10
	v_lshlrev_b32_e32 v14, 16, v11
	v_and_b32_e32 v11, 0xffff0000, v11
	v_add_f32_e32 v14, v16, v14
	v_add_f32_e32 v11, v17, v11
	v_cvt_pk_bf16_f32 v11, v14, v11
	v_lshlrev_b32_e32 v14, 16, v12
	v_and_b32_e32 v12, 0xffff0000, v12
	v_add_f32_e32 v14, v22, v14
	v_add_f32_e32 v12, v23, v12
	v_cvt_pk_bf16_f32 v12, v14, v12
	v_lshlrev_b32_e32 v14, 16, v13
	v_and_b32_e32 v13, 0xffff0000, v13
	v_add_f32_e32 v14, v24, v14
	v_add_f32_e32 v13, v25, v13
	v_and_b32_e32 v15, 0xffff0000, v10
	v_cvt_pk_bf16_f32 v13, v14, v13
	v_lshlrev_b32_e32 v14, 16, v10
	v_mul_f32_e32 v15, v15, v15
	v_lshlrev_b32_e32 v16, 16, v11
	v_fmac_f32_e32 v15, v14, v14
	v_and_b32_e32 v17, 0xffff0000, v11
	v_fmac_f32_e32 v15, v16, v16
	v_lshlrev_b32_e32 v22, 16, v12
	v_fmac_f32_e32 v15, v17, v17
	v_and_b32_e32 v23, 0xffff0000, v12
	v_fmac_f32_e32 v15, v22, v22
	v_lshlrev_b32_e32 v24, 16, v13
	v_fmac_f32_e32 v15, v23, v23
	v_and_b32_e32 v25, 0xffff0000, v13
	v_fmac_f32_e32 v15, v24, v24
	v_fmac_f32_e32 v15, v25, v25
	ds_write_b128 v35, v[10:13] offset:80
	v_add_f32_e32 v22, v26, v15
	ds_read_b128 v[10:13], v1 offset:192
	ds_read_b128 v[14:17], v1 offset:208
	v_lshlrev_b32_e32 v23, 16, v6
	v_and_b32_e32 v6, 0xffff0000, v6
	s_waitcnt lgkmcnt(0)
	v_add_f32_e32 v10, v10, v23
	v_add_f32_e32 v6, v11, v6
	v_cvt_pk_bf16_f32 v6, v10, v6
	v_lshlrev_b32_e32 v10, 16, v7
	v_and_b32_e32 v7, 0xffff0000, v7
	v_add_f32_e32 v10, v12, v10
	v_add_f32_e32 v7, v13, v7
	v_cvt_pk_bf16_f32 v7, v10, v7
	v_lshlrev_b32_e32 v10, 16, v8
	v_and_b32_e32 v8, 0xffff0000, v8
	v_add_f32_e32 v10, v14, v10
	v_add_f32_e32 v8, v15, v8
	v_cvt_pk_bf16_f32 v8, v10, v8
	v_lshlrev_b32_e32 v10, 16, v9
	v_and_b32_e32 v9, 0xffff0000, v9
	v_add_f32_e32 v10, v16, v10
	v_add_f32_e32 v9, v17, v9
	v_and_b32_e32 v11, 0xffff0000, v6
	v_cvt_pk_bf16_f32 v9, v10, v9
	v_lshlrev_b32_e32 v10, 16, v6
	v_mul_f32_e32 v11, v11, v11
	v_lshlrev_b32_e32 v12, 16, v7
	v_fmac_f32_e32 v11, v10, v10
	v_and_b32_e32 v13, 0xffff0000, v7
	v_fmac_f32_e32 v11, v12, v12
	v_lshlrev_b32_e32 v14, 16, v8
	v_fmac_f32_e32 v11, v13, v13
	v_and_b32_e32 v15, 0xffff0000, v8
	v_fmac_f32_e32 v11, v14, v14
	v_lshlrev_b32_e32 v16, 16, v9
	v_fmac_f32_e32 v11, v15, v15
	v_and_b32_e32 v17, 0xffff0000, v9
	v_fmac_f32_e32 v11, v16, v16
	v_fmac_f32_e32 v11, v17, v17
	ds_write_b128 v35, v[6:9] offset:96
	v_add_f32_e32 v14, v22, v11
	ds_read_b128 v[6:9], v1 offset:224
	ds_read_b128 v[10:13], v1 offset:240
	v_lshlrev_b32_e32 v1, 16, v2
	v_and_b32_e32 v2, 0xffff0000, v2
	s_waitcnt lgkmcnt(0)
	v_add_f32_e32 v1, v6, v1
	v_add_f32_e32 v2, v7, v2
	v_cvt_pk_bf16_f32 v2, v1, v2
	v_lshlrev_b32_e32 v1, 16, v3
	v_and_b32_e32 v3, 0xffff0000, v3
	v_add_f32_e32 v1, v8, v1
	v_add_f32_e32 v3, v9, v3
	v_cvt_pk_bf16_f32 v3, v1, v3
	v_lshlrev_b32_e32 v1, 16, v4
	v_and_b32_e32 v4, 0xffff0000, v4
	v_add_f32_e32 v1, v10, v1
	v_add_f32_e32 v4, v11, v4
	v_cvt_pk_bf16_f32 v4, v1, v4
	v_lshlrev_b32_e32 v1, 16, v5
	v_and_b32_e32 v5, 0xffff0000, v5
	v_add_f32_e32 v1, v12, v1
	v_add_f32_e32 v5, v13, v5
	v_and_b32_e32 v6, 0xffff0000, v2
	v_cvt_pk_bf16_f32 v5, v1, v5
	v_lshlrev_b32_e32 v1, 16, v2
	v_mul_f32_e32 v6, v6, v6
	v_lshlrev_b32_e32 v7, 16, v3
	v_fmac_f32_e32 v6, v1, v1
	v_and_b32_e32 v8, 0xffff0000, v3
	v_fmac_f32_e32 v6, v7, v7
	v_lshlrev_b32_e32 v9, 16, v4
	v_fmac_f32_e32 v6, v8, v8
	v_and_b32_e32 v10, 0xffff0000, v4
	v_fmac_f32_e32 v6, v9, v9
	v_lshlrev_b32_e32 v11, 16, v5
	v_fmac_f32_e32 v6, v10, v10
	v_and_b32_e32 v12, 0xffff0000, v5
	v_fmac_f32_e32 v6, v11, v11
	ds_write_b128 v35, v[2:5] offset:112
	v_and_b32_e32 v7, 63, v170
	v_lshrrev_b32_e32 v13, 3, v7
	v_sub_u32_e32 v13, v13, v7
	v_and_b32_e32 v7, 7, v7
	v_lshlrev_b32_e32 v7, 4, v7
	v_mul_i32_i24_e32 v2, 0x800, v13
	v_add_u32_e32 v2, v2, v7
	v_mul_i32_i24_e32 v13, 0x110, v13
	v_add3_u32 v13, v13, v7, v35
	s_waitcnt lgkmcnt(0)
	ds_read_b128 v[8:11], v13 offset:0
	v_mov_b32_e32 v4, v2
	v_ashrrev_i32_e32 v5, 31, v4
	v_lshl_add_u64 v[16:17], v[4:5], 0, v[20:21]
	s_waitcnt lgkmcnt(0)
	global_store_dwordx4 v[16:17], v[8:11], off offset:128
	ds_read_b128 v[24:27], v13 offset:2176
	v_add_u32_e32 v4, 0x4000, v2
	v_ashrrev_i32_e32 v5, 31, v4
	v_lshl_add_u64 v[16:17], v[4:5], 0, v[20:21]
	s_waitcnt lgkmcnt(0)
	global_store_dwordx4 v[16:17], v[24:27], off offset:128
	ds_read_b128 v[8:11], v13 offset:4352
	v_add_u32_e32 v4, 0x8000, v2
	v_ashrrev_i32_e32 v5, 31, v4
	v_lshl_add_u64 v[16:17], v[4:5], 0, v[20:21]
	s_waitcnt lgkmcnt(0)
	global_store_dwordx4 v[16:17], v[8:11], off offset:128
	ds_read_b128 v[24:27], v13 offset:6528
	v_add_u32_e32 v4, 0xc000, v2
	v_ashrrev_i32_e32 v5, 31, v4
	v_lshl_add_u64 v[16:17], v[4:5], 0, v[20:21]
	s_waitcnt lgkmcnt(0)
	global_store_dwordx4 v[16:17], v[24:27], off offset:128
	ds_read_b128 v[8:11], v13 offset:8704
	v_add_u32_e32 v4, 0x10000, v2
	v_ashrrev_i32_e32 v5, 31, v4
	v_lshl_add_u64 v[16:17], v[4:5], 0, v[20:21]
	s_waitcnt lgkmcnt(0)
	global_store_dwordx4 v[16:17], v[8:11], off offset:128
	ds_read_b128 v[24:27], v13 offset:10880
	v_add_u32_e32 v4, 0x14000, v2
	v_ashrrev_i32_e32 v5, 31, v4
	v_lshl_add_u64 v[16:17], v[4:5], 0, v[20:21]
	s_waitcnt lgkmcnt(0)
	global_store_dwordx4 v[16:17], v[24:27], off offset:128
	ds_read_b128 v[8:11], v13 offset:13056
	v_add_u32_e32 v4, 0x18000, v2
	v_ashrrev_i32_e32 v5, 31, v4
	v_lshl_add_u64 v[16:17], v[4:5], 0, v[20:21]
	s_waitcnt lgkmcnt(0)
	global_store_dwordx4 v[16:17], v[8:11], off offset:128
	ds_read_b128 v[24:27], v13 offset:15232
	v_add_u32_e32 v4, 0x1c000, v2
	v_ashrrev_i32_e32 v5, 31, v4
	v_lshl_add_u64 v[16:17], v[4:5], 0, v[20:21]
	s_waitcnt lgkmcnt(0)
	global_store_dwordx4 v[16:17], v[24:27], off offset:128
	v_fmac_f32_e32 v6, v12, v12
	v_add_f32_e32 v1, v14, v6
	v_lshlrev_b64 v[2:3], 6, v[18:19]
	v_lshl_add_u64 v[2:3], s[6:7], 0, v[2:3]
	v_lshl_add_u64 v[2:3], v[2:3], 0, s[16:17]
	flat_store_dword v[2:3], v1 offset:4
	s_branch .LBB0_522
